# hand-written GEMM3 epilogue, unitCF body, GEMM2 combine path; final barrier skipped
# speedup vs baseline: 1.0255x; 1.0170x over previous
.LBB0_388:
	v_mov_b32_e32 v12, v11
	v_lshlrev_b32_e32 v40, 11, v12
	v_lshl_add_u32 v40, v10, 2, v40
	v_mad_u32_u24 v41, v12, s66, v0
	v_lshlrev_b32_e32 v42, 10, v12
	v_lshl_add_u32 v42, v10, 1, v42
	s_add_u32 s0, s4, 0x823fa00
	s_addc_u32 s1, s5, 0
	s_add_u32 s0, s0, s64
	s_addc_u32 s1, s1, 0
	global_load_dwordx4 v[44:47], v40, s[6:7]
	global_load_dwordx4 v[48:51], v40, s[6:7] offset:16
	global_load_dwordx4 v[52:55], v40, s[8:9]
	global_load_dwordx4 v[56:59], v40, s[8:9] offset:16
	global_load_dwordx4 v[60:63], v41, s[0:1]
	v_add_u32_e32 v43, 0x2000, v40
	global_load_dwordx4 v[64:67], v43, s[6:7]
	global_load_dwordx4 v[68:71], v43, s[6:7] offset:16
	global_load_dwordx4 v[72:75], v43, s[8:9]
	global_load_dwordx4 v[76:79], v43, s[8:9] offset:16
	v_add_u32_e32 v43, 0x7800, v41
	global_load_dwordx4 v[80:83], v43, s[0:1]
	v_add_u32_e32 v43, 0x4000, v40
	global_load_dwordx4 v[84:87], v43, s[6:7]
	global_load_dwordx4 v[88:91], v43, s[6:7] offset:16
	global_load_dwordx4 v[92:95], v43, s[8:9]
	global_load_dwordx4 v[96:99], v43, s[8:9] offset:16
	v_add_u32_e32 v43, 0xf000, v41
	global_load_dwordx4 v[100:103], v43, s[0:1]
	v_add_u32_e32 v43, 0x6000, v40
	global_load_dwordx4 v[104:107], v43, s[6:7]
	global_load_dwordx4 v[108:111], v43, s[6:7] offset:16
	global_load_dwordx4 v[112:115], v43, s[8:9]
	global_load_dwordx4 v[116:119], v43, s[8:9] offset:16
	v_add_u32_e32 v43, 0x16800, v41
	global_load_dwordx4 v[120:123], v43, s[0:1]
	v_add_u32_e32 v43, 0x8000, v40
	global_load_dwordx4 v[124:127], v43, s[6:7]
	global_load_dwordx4 v[128:131], v43, s[6:7] offset:16
	global_load_dwordx4 v[132:135], v43, s[8:9]
	global_load_dwordx4 v[136:139], v43, s[8:9] offset:16
	v_add_u32_e32 v43, 0x1e000, v41
	global_load_dwordx4 v[140:143], v43, s[0:1]
	v_add_u32_e32 v43, 0xa000, v40
	global_load_dwordx4 v[144:147], v43, s[6:7]
	global_load_dwordx4 v[148:151], v43, s[6:7] offset:16
	global_load_dwordx4 v[152:155], v43, s[8:9]
	global_load_dwordx4 v[156:159], v43, s[8:9] offset:16
	v_add_u32_e32 v43, 0x25800, v41
	global_load_dwordx4 v[160:163], v43, s[0:1]
	v_add_u32_e32 v43, 0xc000, v40
	global_load_dwordx4 v[164:167], v43, s[6:7]
	global_load_dwordx4 v[168:171], v43, s[6:7] offset:16
	global_load_dwordx4 v[172:175], v43, s[8:9]
	global_load_dwordx4 v[176:179], v43, s[8:9] offset:16
	v_add_u32_e32 v43, 0x2d000, v41
	global_load_dwordx4 v[180:183], v43, s[0:1]
	v_add_u32_e32 v43, 0xe000, v40
	global_load_dwordx4 v[184:187], v43, s[6:7]
	global_load_dwordx4 v[188:191], v43, s[6:7] offset:16
	global_load_dwordx4 v[192:195], v43, s[8:9]
	global_load_dwordx4 v[202:205], v43, s[8:9] offset:16
	v_add_u32_e32 v43, 0x34800, v41
	global_load_dwordx4 v[206:209], v43, s[0:1]
	s_waitcnt vmcnt(35)
	v_pk_add_f32 v[44:45], v[44:45], v[52:53]
	v_pk_add_f32 v[46:47], v[46:47], v[54:55]
	v_pk_add_f32 v[48:49], v[48:49], v[56:57]
	v_pk_add_f32 v[50:51], v[50:51], v[58:59]
	v_add_f32_e32 v12, v44, v45
	v_add_f32_e32 v13, v48, v49
	v_add_f32_e32 v14, v46, v47
	v_add_f32_e32 v15, v50, v51
	v_add_f32_e32 v12, v12, v14
	v_add_f32_e32 v13, v13, v15
	v_add_f32_e32 v12, v12, v13
	s_nop 1
	v_add_f32_dpp v12, v12, v12 row_ror:8 row_mask:0xf bank_mask:0xf
	s_nop 1
	v_add_f32_dpp v12, v12, v12 row_ror:4 row_mask:0xf bank_mask:0xf
	s_nop 1
	v_add_f32_dpp v12, v12, v12 row_ror:2 row_mask:0xf bank_mask:0xf
	s_nop 1
	v_add_f32_dpp v12, v12, v12 row_ror:1 row_mask:0xf bank_mask:0xf
	v_fmac_f32_e32 v44, 0xbc000000, v12
	v_fmac_f32_e32 v45, 0xbc000000, v12
	v_fmac_f32_e32 v46, 0xbc000000, v12
	v_fmac_f32_e32 v47, 0xbc000000, v12
	v_fmac_f32_e32 v48, 0xbc000000, v12
	v_fmac_f32_e32 v49, 0xbc000000, v12
	v_fmac_f32_e32 v50, 0xbc000000, v12
	v_fmac_f32_e32 v51, 0xbc000000, v12
	v_mul_f32_e32 v13, v45, v45
	v_mul_f32_e32 v14, v49, v49
	v_mul_f32_e32 v15, v47, v47
	v_mul_f32_e32 v16, v51, v51
	v_fma_f32 v13, v44, v44, v13
	v_fma_f32 v14, v48, v48, v14
	v_fma_f32 v15, v46, v46, v15
	v_fma_f32 v16, v50, v50, v16
	v_add_f32_e32 v13, v13, v15
	v_add_f32_e32 v14, v14, v16
	v_add_f32_e32 v13, v13, v14
	s_nop 1
	v_add_f32_dpp v13, v13, v13 row_ror:8 row_mask:0xf bank_mask:0xf
	s_nop 1
	v_add_f32_dpp v13, v13, v13 row_ror:4 row_mask:0xf bank_mask:0xf
	s_nop 1
	v_add_f32_dpp v13, v13, v13 row_ror:2 row_mask:0xf bank_mask:0xf
	s_nop 1
	v_add_f32_dpp v13, v13, v13 row_ror:1 row_mask:0xf bank_mask:0xf
	v_lshlrev_b32_e32 v20, 16, v60
	v_and_b32_e32 v21, 0xffff0000, v60
	v_lshlrev_b32_e32 v22, 16, v61
	v_and_b32_e32 v23, 0xffff0000, v61
	v_lshlrev_b32_e32 v24, 16, v62
	v_and_b32_e32 v25, 0xffff0000, v62
	v_lshlrev_b32_e32 v26, 16, v63
	v_and_b32_e32 v27, 0xffff0000, v63
	v_mul_f32_e32 v28, 0xbfb8aa3b, v20
	v_mul_f32_e32 v29, 0xbfb8aa3b, v21
	v_mul_f32_e32 v30, 0xbfb8aa3b, v22
	v_mul_f32_e32 v31, 0xbfb8aa3b, v23
	v_mul_f32_e32 v32, 0xbfb8aa3b, v24
	v_mul_f32_e32 v33, 0xbfb8aa3b, v25
	v_mul_f32_e32 v34, 0xbfb8aa3b, v26
	v_mul_f32_e32 v35, 0xbfb8aa3b, v27
	v_exp_f32_e32 v28, v28
	v_exp_f32_e32 v29, v29
	v_exp_f32_e32 v30, v30
	v_exp_f32_e32 v31, v31
	v_exp_f32_e32 v32, v32
	v_exp_f32_e32 v33, v33
	v_exp_f32_e32 v34, v34
	v_exp_f32_e32 v35, v35
	v_fmamk_f32 v13, v13, 0x3c000000, v238
	v_cmp_gt_f32_e32 vcc, s67, v13
	v_mul_f32_e32 v14, 0x4b800000, v13
	s_nop 0
	v_cndmask_b32_e32 v13, v13, v14, vcc
	v_rsq_f32_e32 v13, v13
	v_add_f32_e32 v28, 1.0, v28
	v_add_f32_e32 v29, 1.0, v29
	v_add_f32_e32 v30, 1.0, v30
	v_add_f32_e32 v31, 1.0, v31
	v_add_f32_e32 v32, 1.0, v32
	v_add_f32_e32 v33, 1.0, v33
	v_add_f32_e32 v34, 1.0, v34
	v_add_f32_e32 v35, 1.0, v35
	v_rcp_f32_e32 v28, v28
	v_rcp_f32_e32 v29, v29
	v_rcp_f32_e32 v30, v30
	v_rcp_f32_e32 v31, v31
	v_rcp_f32_e32 v32, v32
	v_rcp_f32_e32 v33, v33
	v_rcp_f32_e32 v34, v34
	v_rcp_f32_e32 v35, v35
	v_mul_f32_e32 v14, 0x45800000, v13
	s_nop 0
	v_cndmask_b32_e32 v36, v13, v14, vcc
	v_pk_mul_f32 v[20:21], v[28:29], v[20:21]
	v_pk_mul_f32 v[22:23], v[30:31], v[22:23]
	v_pk_mul_f32 v[24:25], v[32:33], v[24:25]
	v_pk_mul_f32 v[26:27], v[34:35], v[26:27]
	v_pk_mul_f32 v[44:45], v[44:45], v[36:37] op_sel_hi:[1,0]
	v_pk_mul_f32 v[46:47], v[46:47], v[36:37] op_sel_hi:[1,0]
	v_pk_mul_f32 v[48:49], v[48:49], v[36:37] op_sel_hi:[1,0]
	v_pk_mul_f32 v[50:51], v[50:51], v[36:37] op_sel_hi:[1,0]
	v_pk_mul_f32 v[44:45], v[6:7], v[44:45]
	v_pk_mul_f32 v[46:47], v[8:9], v[46:47]
	v_pk_mul_f32 v[48:49], v[2:3], v[48:49]
	v_pk_mul_f32 v[50:51], v[4:5], v[50:51]
	v_pk_mul_f32 v[44:45], v[20:21], v[44:45]
	v_pk_mul_f32 v[46:47], v[22:23], v[46:47]
	v_pk_mul_f32 v[48:49], v[24:25], v[48:49]
	v_pk_mul_f32 v[50:51], v[26:27], v[50:51]
	v_cvt_pk_bf16_f32 v16, v44, v45
	v_cvt_pk_bf16_f32 v17, v46, v47
	v_cvt_pk_bf16_f32 v18, v48, v49
	v_cvt_pk_bf16_f32 v19, v50, v51
	global_store_dwordx4 v42, v[16:19], s[10:11]
	s_waitcnt vmcnt(31)
	v_pk_add_f32 v[64:65], v[64:65], v[72:73]
	v_pk_add_f32 v[66:67], v[66:67], v[74:75]
	v_pk_add_f32 v[68:69], v[68:69], v[76:77]
	v_pk_add_f32 v[70:71], v[70:71], v[78:79]
	v_add_f32_e32 v12, v64, v65
	v_add_f32_e32 v13, v68, v69
	v_add_f32_e32 v14, v66, v67
	v_add_f32_e32 v15, v70, v71
	v_add_f32_e32 v12, v12, v14
	v_add_f32_e32 v13, v13, v15
	v_add_f32_e32 v12, v12, v13
	s_nop 1
	v_add_f32_dpp v12, v12, v12 row_ror:8 row_mask:0xf bank_mask:0xf
	s_nop 1
	v_add_f32_dpp v12, v12, v12 row_ror:4 row_mask:0xf bank_mask:0xf
	s_nop 1
	v_add_f32_dpp v12, v12, v12 row_ror:2 row_mask:0xf bank_mask:0xf
	s_nop 1
	v_add_f32_dpp v12, v12, v12 row_ror:1 row_mask:0xf bank_mask:0xf
	v_fmac_f32_e32 v64, 0xbc000000, v12
	v_fmac_f32_e32 v65, 0xbc000000, v12
	v_fmac_f32_e32 v66, 0xbc000000, v12
	v_fmac_f32_e32 v67, 0xbc000000, v12
	v_fmac_f32_e32 v68, 0xbc000000, v12
	v_fmac_f32_e32 v69, 0xbc000000, v12
	v_fmac_f32_e32 v70, 0xbc000000, v12
	v_fmac_f32_e32 v71, 0xbc000000, v12
	v_mul_f32_e32 v13, v65, v65
	v_mul_f32_e32 v14, v69, v69
	v_mul_f32_e32 v15, v67, v67
	v_mul_f32_e32 v16, v71, v71
	v_fma_f32 v13, v64, v64, v13
	v_fma_f32 v14, v68, v68, v14
	v_fma_f32 v15, v66, v66, v15
	v_fma_f32 v16, v70, v70, v16
	v_add_f32_e32 v13, v13, v15
	v_add_f32_e32 v14, v14, v16
	v_add_f32_e32 v13, v13, v14
	s_nop 1
	v_add_f32_dpp v13, v13, v13 row_ror:8 row_mask:0xf bank_mask:0xf
	s_nop 1
	v_add_f32_dpp v13, v13, v13 row_ror:4 row_mask:0xf bank_mask:0xf
	s_nop 1
	v_add_f32_dpp v13, v13, v13 row_ror:2 row_mask:0xf bank_mask:0xf
	s_nop 1
	v_add_f32_dpp v13, v13, v13 row_ror:1 row_mask:0xf bank_mask:0xf
	v_lshlrev_b32_e32 v20, 16, v80
	v_and_b32_e32 v21, 0xffff0000, v80
	v_lshlrev_b32_e32 v22, 16, v81
	v_and_b32_e32 v23, 0xffff0000, v81
	v_lshlrev_b32_e32 v24, 16, v82
	v_and_b32_e32 v25, 0xffff0000, v82
	v_lshlrev_b32_e32 v26, 16, v83
	v_and_b32_e32 v27, 0xffff0000, v83
	v_mul_f32_e32 v28, 0xbfb8aa3b, v20
	v_mul_f32_e32 v29, 0xbfb8aa3b, v21
	v_mul_f32_e32 v30, 0xbfb8aa3b, v22
	v_mul_f32_e32 v31, 0xbfb8aa3b, v23
	v_mul_f32_e32 v32, 0xbfb8aa3b, v24
	v_mul_f32_e32 v33, 0xbfb8aa3b, v25
	v_mul_f32_e32 v34, 0xbfb8aa3b, v26
	v_mul_f32_e32 v35, 0xbfb8aa3b, v27
	v_exp_f32_e32 v28, v28
	v_exp_f32_e32 v29, v29
	v_exp_f32_e32 v30, v30
	v_exp_f32_e32 v31, v31
	v_exp_f32_e32 v32, v32
	v_exp_f32_e32 v33, v33
	v_exp_f32_e32 v34, v34
	v_exp_f32_e32 v35, v35
	v_fmamk_f32 v13, v13, 0x3c000000, v238
	v_cmp_gt_f32_e32 vcc, s67, v13
	v_mul_f32_e32 v14, 0x4b800000, v13
	s_nop 0
	v_cndmask_b32_e32 v13, v13, v14, vcc
	v_rsq_f32_e32 v13, v13
	v_add_f32_e32 v28, 1.0, v28
	v_add_f32_e32 v29, 1.0, v29
	v_add_f32_e32 v30, 1.0, v30
	v_add_f32_e32 v31, 1.0, v31
	v_add_f32_e32 v32, 1.0, v32
	v_add_f32_e32 v33, 1.0, v33
	v_add_f32_e32 v34, 1.0, v34
	v_add_f32_e32 v35, 1.0, v35
	v_rcp_f32_e32 v28, v28
	v_rcp_f32_e32 v29, v29
	v_rcp_f32_e32 v30, v30
	v_rcp_f32_e32 v31, v31
	v_rcp_f32_e32 v32, v32
	v_rcp_f32_e32 v33, v33
	v_rcp_f32_e32 v34, v34
	v_rcp_f32_e32 v35, v35
	v_mul_f32_e32 v14, 0x45800000, v13
	s_nop 0
	v_cndmask_b32_e32 v36, v13, v14, vcc
	v_pk_mul_f32 v[20:21], v[28:29], v[20:21]
	v_pk_mul_f32 v[22:23], v[30:31], v[22:23]
	v_pk_mul_f32 v[24:25], v[32:33], v[24:25]
	v_pk_mul_f32 v[26:27], v[34:35], v[26:27]
	v_pk_mul_f32 v[64:65], v[64:65], v[36:37] op_sel_hi:[1,0]
	v_pk_mul_f32 v[66:67], v[66:67], v[36:37] op_sel_hi:[1,0]
	v_pk_mul_f32 v[68:69], v[68:69], v[36:37] op_sel_hi:[1,0]
	v_pk_mul_f32 v[70:71], v[70:71], v[36:37] op_sel_hi:[1,0]
	v_pk_mul_f32 v[64:65], v[6:7], v[64:65]
	v_pk_mul_f32 v[66:67], v[8:9], v[66:67]
	v_pk_mul_f32 v[68:69], v[2:3], v[68:69]
	v_pk_mul_f32 v[70:71], v[4:5], v[70:71]
	v_pk_mul_f32 v[64:65], v[20:21], v[64:65]
	v_pk_mul_f32 v[66:67], v[22:23], v[66:67]
	v_pk_mul_f32 v[68:69], v[24:25], v[68:69]
	v_pk_mul_f32 v[70:71], v[26:27], v[70:71]
	v_cvt_pk_bf16_f32 v16, v64, v65
	v_cvt_pk_bf16_f32 v17, v66, v67
	v_cvt_pk_bf16_f32 v18, v68, v69
	v_cvt_pk_bf16_f32 v19, v70, v71
	v_add_u32_e32 v43, 0x1000, v42
	global_store_dwordx4 v43, v[16:19], s[10:11]
	s_waitcnt vmcnt(27)
	v_pk_add_f32 v[84:85], v[84:85], v[92:93]
	v_pk_add_f32 v[86:87], v[86:87], v[94:95]
	v_pk_add_f32 v[88:89], v[88:89], v[96:97]
	v_pk_add_f32 v[90:91], v[90:91], v[98:99]
	v_add_f32_e32 v12, v84, v85
	v_add_f32_e32 v13, v88, v89
	v_add_f32_e32 v14, v86, v87
	v_add_f32_e32 v15, v90, v91
	v_add_f32_e32 v12, v12, v14
	v_add_f32_e32 v13, v13, v15
	v_add_f32_e32 v12, v12, v13
	s_nop 1
	v_add_f32_dpp v12, v12, v12 row_ror:8 row_mask:0xf bank_mask:0xf
	s_nop 1
	v_add_f32_dpp v12, v12, v12 row_ror:4 row_mask:0xf bank_mask:0xf
	s_nop 1
	v_add_f32_dpp v12, v12, v12 row_ror:2 row_mask:0xf bank_mask:0xf
	s_nop 1
	v_add_f32_dpp v12, v12, v12 row_ror:1 row_mask:0xf bank_mask:0xf
	v_fmac_f32_e32 v84, 0xbc000000, v12
	v_fmac_f32_e32 v85, 0xbc000000, v12
	v_fmac_f32_e32 v86, 0xbc000000, v12
	v_fmac_f32_e32 v87, 0xbc000000, v12
	v_fmac_f32_e32 v88, 0xbc000000, v12
	v_fmac_f32_e32 v89, 0xbc000000, v12
	v_fmac_f32_e32 v90, 0xbc000000, v12
	v_fmac_f32_e32 v91, 0xbc000000, v12
	v_mul_f32_e32 v13, v85, v85
	v_mul_f32_e32 v14, v89, v89
	v_mul_f32_e32 v15, v87, v87
	v_mul_f32_e32 v16, v91, v91
	v_fma_f32 v13, v84, v84, v13
	v_fma_f32 v14, v88, v88, v14
	v_fma_f32 v15, v86, v86, v15
	v_fma_f32 v16, v90, v90, v16
	v_add_f32_e32 v13, v13, v15
	v_add_f32_e32 v14, v14, v16
	v_add_f32_e32 v13, v13, v14
	s_nop 1
	v_add_f32_dpp v13, v13, v13 row_ror:8 row_mask:0xf bank_mask:0xf
	s_nop 1
	v_add_f32_dpp v13, v13, v13 row_ror:4 row_mask:0xf bank_mask:0xf
	s_nop 1
	v_add_f32_dpp v13, v13, v13 row_ror:2 row_mask:0xf bank_mask:0xf
	s_nop 1
	v_add_f32_dpp v13, v13, v13 row_ror:1 row_mask:0xf bank_mask:0xf
	v_lshlrev_b32_e32 v20, 16, v100
	v_and_b32_e32 v21, 0xffff0000, v100
	v_lshlrev_b32_e32 v22, 16, v101
	v_and_b32_e32 v23, 0xffff0000, v101
	v_lshlrev_b32_e32 v24, 16, v102
	v_and_b32_e32 v25, 0xffff0000, v102
	v_lshlrev_b32_e32 v26, 16, v103
	v_and_b32_e32 v27, 0xffff0000, v103
	v_mul_f32_e32 v28, 0xbfb8aa3b, v20
	v_mul_f32_e32 v29, 0xbfb8aa3b, v21
	v_mul_f32_e32 v30, 0xbfb8aa3b, v22
	v_mul_f32_e32 v31, 0xbfb8aa3b, v23
	v_mul_f32_e32 v32, 0xbfb8aa3b, v24
	v_mul_f32_e32 v33, 0xbfb8aa3b, v25
	v_mul_f32_e32 v34, 0xbfb8aa3b, v26
	v_mul_f32_e32 v35, 0xbfb8aa3b, v27
	v_exp_f32_e32 v28, v28
	v_exp_f32_e32 v29, v29
	v_exp_f32_e32 v30, v30
	v_exp_f32_e32 v31, v31
	v_exp_f32_e32 v32, v32
	v_exp_f32_e32 v33, v33
	v_exp_f32_e32 v34, v34
	v_exp_f32_e32 v35, v35
	v_fmamk_f32 v13, v13, 0x3c000000, v238
	v_cmp_gt_f32_e32 vcc, s67, v13
	v_mul_f32_e32 v14, 0x4b800000, v13
	s_nop 0
	v_cndmask_b32_e32 v13, v13, v14, vcc
	v_rsq_f32_e32 v13, v13
	v_add_f32_e32 v28, 1.0, v28
	v_add_f32_e32 v29, 1.0, v29
	v_add_f32_e32 v30, 1.0, v30
	v_add_f32_e32 v31, 1.0, v31
	v_add_f32_e32 v32, 1.0, v32
	v_add_f32_e32 v33, 1.0, v33
	v_add_f32_e32 v34, 1.0, v34
	v_add_f32_e32 v35, 1.0, v35
	v_rcp_f32_e32 v28, v28
	v_rcp_f32_e32 v29, v29
	v_rcp_f32_e32 v30, v30
	v_rcp_f32_e32 v31, v31
	v_rcp_f32_e32 v32, v32
	v_rcp_f32_e32 v33, v33
	v_rcp_f32_e32 v34, v34
	v_rcp_f32_e32 v35, v35
	v_mul_f32_e32 v14, 0x45800000, v13
	s_nop 0
	v_cndmask_b32_e32 v36, v13, v14, vcc
	v_pk_mul_f32 v[20:21], v[28:29], v[20:21]
	v_pk_mul_f32 v[22:23], v[30:31], v[22:23]
	v_pk_mul_f32 v[24:25], v[32:33], v[24:25]
	v_pk_mul_f32 v[26:27], v[34:35], v[26:27]
	v_pk_mul_f32 v[84:85], v[84:85], v[36:37] op_sel_hi:[1,0]
	v_pk_mul_f32 v[86:87], v[86:87], v[36:37] op_sel_hi:[1,0]
	v_pk_mul_f32 v[88:89], v[88:89], v[36:37] op_sel_hi:[1,0]
	v_pk_mul_f32 v[90:91], v[90:91], v[36:37] op_sel_hi:[1,0]
	v_pk_mul_f32 v[84:85], v[6:7], v[84:85]
	v_pk_mul_f32 v[86:87], v[8:9], v[86:87]
	v_pk_mul_f32 v[88:89], v[2:3], v[88:89]
	v_pk_mul_f32 v[90:91], v[4:5], v[90:91]
	v_pk_mul_f32 v[84:85], v[20:21], v[84:85]
	v_pk_mul_f32 v[86:87], v[22:23], v[86:87]
	v_pk_mul_f32 v[88:89], v[24:25], v[88:89]
	v_pk_mul_f32 v[90:91], v[26:27], v[90:91]
	v_cvt_pk_bf16_f32 v16, v84, v85
	v_cvt_pk_bf16_f32 v17, v86, v87
	v_cvt_pk_bf16_f32 v18, v88, v89
	v_cvt_pk_bf16_f32 v19, v90, v91
	v_add_u32_e32 v43, 0x2000, v42
	global_store_dwordx4 v43, v[16:19], s[10:11]
	s_waitcnt vmcnt(23)
	v_pk_add_f32 v[104:105], v[104:105], v[112:113]
	v_pk_add_f32 v[106:107], v[106:107], v[114:115]
	v_pk_add_f32 v[108:109], v[108:109], v[116:117]
	v_pk_add_f32 v[110:111], v[110:111], v[118:119]
	v_add_f32_e32 v12, v104, v105
	v_add_f32_e32 v13, v108, v109
	v_add_f32_e32 v14, v106, v107
	v_add_f32_e32 v15, v110, v111
	v_add_f32_e32 v12, v12, v14
	v_add_f32_e32 v13, v13, v15
	v_add_f32_e32 v12, v12, v13
	s_nop 1
	v_add_f32_dpp v12, v12, v12 row_ror:8 row_mask:0xf bank_mask:0xf
	s_nop 1
	v_add_f32_dpp v12, v12, v12 row_ror:4 row_mask:0xf bank_mask:0xf
	s_nop 1
	v_add_f32_dpp v12, v12, v12 row_ror:2 row_mask:0xf bank_mask:0xf
	s_nop 1
	v_add_f32_dpp v12, v12, v12 row_ror:1 row_mask:0xf bank_mask:0xf
	v_fmac_f32_e32 v104, 0xbc000000, v12
	v_fmac_f32_e32 v105, 0xbc000000, v12
	v_fmac_f32_e32 v106, 0xbc000000, v12
	v_fmac_f32_e32 v107, 0xbc000000, v12
	v_fmac_f32_e32 v108, 0xbc000000, v12
	v_fmac_f32_e32 v109, 0xbc000000, v12
	v_fmac_f32_e32 v110, 0xbc000000, v12
	v_fmac_f32_e32 v111, 0xbc000000, v12
	v_mul_f32_e32 v13, v105, v105
	v_mul_f32_e32 v14, v109, v109
	v_mul_f32_e32 v15, v107, v107
	v_mul_f32_e32 v16, v111, v111
	v_fma_f32 v13, v104, v104, v13
	v_fma_f32 v14, v108, v108, v14
	v_fma_f32 v15, v106, v106, v15
	v_fma_f32 v16, v110, v110, v16
	v_add_f32_e32 v13, v13, v15
	v_add_f32_e32 v14, v14, v16
	v_add_f32_e32 v13, v13, v14
	s_nop 1
	v_add_f32_dpp v13, v13, v13 row_ror:8 row_mask:0xf bank_mask:0xf
	s_nop 1
	v_add_f32_dpp v13, v13, v13 row_ror:4 row_mask:0xf bank_mask:0xf
	s_nop 1
	v_add_f32_dpp v13, v13, v13 row_ror:2 row_mask:0xf bank_mask:0xf
	s_nop 1
	v_add_f32_dpp v13, v13, v13 row_ror:1 row_mask:0xf bank_mask:0xf
	v_lshlrev_b32_e32 v20, 16, v120
	v_and_b32_e32 v21, 0xffff0000, v120
	v_lshlrev_b32_e32 v22, 16, v121
	v_and_b32_e32 v23, 0xffff0000, v121
	v_lshlrev_b32_e32 v24, 16, v122
	v_and_b32_e32 v25, 0xffff0000, v122
	v_lshlrev_b32_e32 v26, 16, v123
	v_and_b32_e32 v27, 0xffff0000, v123
	v_mul_f32_e32 v28, 0xbfb8aa3b, v20
	v_mul_f32_e32 v29, 0xbfb8aa3b, v21
	v_mul_f32_e32 v30, 0xbfb8aa3b, v22
	v_mul_f32_e32 v31, 0xbfb8aa3b, v23
	v_mul_f32_e32 v32, 0xbfb8aa3b, v24
	v_mul_f32_e32 v33, 0xbfb8aa3b, v25
	v_mul_f32_e32 v34, 0xbfb8aa3b, v26
	v_mul_f32_e32 v35, 0xbfb8aa3b, v27
	v_exp_f32_e32 v28, v28
	v_exp_f32_e32 v29, v29
	v_exp_f32_e32 v30, v30
	v_exp_f32_e32 v31, v31
	v_exp_f32_e32 v32, v32
	v_exp_f32_e32 v33, v33
	v_exp_f32_e32 v34, v34
	v_exp_f32_e32 v35, v35
	v_fmamk_f32 v13, v13, 0x3c000000, v238
	v_cmp_gt_f32_e32 vcc, s67, v13
	v_mul_f32_e32 v14, 0x4b800000, v13
	s_nop 0
	v_cndmask_b32_e32 v13, v13, v14, vcc
	v_rsq_f32_e32 v13, v13
	v_add_f32_e32 v28, 1.0, v28
	v_add_f32_e32 v29, 1.0, v29
	v_add_f32_e32 v30, 1.0, v30
	v_add_f32_e32 v31, 1.0, v31
	v_add_f32_e32 v32, 1.0, v32
	v_add_f32_e32 v33, 1.0, v33
	v_add_f32_e32 v34, 1.0, v34
	v_add_f32_e32 v35, 1.0, v35
	v_rcp_f32_e32 v28, v28
	v_rcp_f32_e32 v29, v29
	v_rcp_f32_e32 v30, v30
	v_rcp_f32_e32 v31, v31
	v_rcp_f32_e32 v32, v32
	v_rcp_f32_e32 v33, v33
	v_rcp_f32_e32 v34, v34
	v_rcp_f32_e32 v35, v35
	v_mul_f32_e32 v14, 0x45800000, v13
	s_nop 0
	v_cndmask_b32_e32 v36, v13, v14, vcc
	v_pk_mul_f32 v[20:21], v[28:29], v[20:21]
	v_pk_mul_f32 v[22:23], v[30:31], v[22:23]
	v_pk_mul_f32 v[24:25], v[32:33], v[24:25]
	v_pk_mul_f32 v[26:27], v[34:35], v[26:27]
	v_pk_mul_f32 v[104:105], v[104:105], v[36:37] op_sel_hi:[1,0]
	v_pk_mul_f32 v[106:107], v[106:107], v[36:37] op_sel_hi:[1,0]
	v_pk_mul_f32 v[108:109], v[108:109], v[36:37] op_sel_hi:[1,0]
	v_pk_mul_f32 v[110:111], v[110:111], v[36:37] op_sel_hi:[1,0]
	v_pk_mul_f32 v[104:105], v[6:7], v[104:105]
	v_pk_mul_f32 v[106:107], v[8:9], v[106:107]
	v_pk_mul_f32 v[108:109], v[2:3], v[108:109]
	v_pk_mul_f32 v[110:111], v[4:5], v[110:111]
	v_pk_mul_f32 v[104:105], v[20:21], v[104:105]
	v_pk_mul_f32 v[106:107], v[22:23], v[106:107]
	v_pk_mul_f32 v[108:109], v[24:25], v[108:109]
	v_pk_mul_f32 v[110:111], v[26:27], v[110:111]
	v_cvt_pk_bf16_f32 v16, v104, v105
	v_cvt_pk_bf16_f32 v17, v106, v107
	v_cvt_pk_bf16_f32 v18, v108, v109
	v_cvt_pk_bf16_f32 v19, v110, v111
	v_add_u32_e32 v43, 0x3000, v42
	global_store_dwordx4 v43, v[16:19], s[10:11]
	s_waitcnt vmcnt(19)
	v_pk_add_f32 v[124:125], v[124:125], v[132:133]
	v_pk_add_f32 v[126:127], v[126:127], v[134:135]
	v_pk_add_f32 v[128:129], v[128:129], v[136:137]
	v_pk_add_f32 v[130:131], v[130:131], v[138:139]
	v_add_f32_e32 v12, v124, v125
	v_add_f32_e32 v13, v128, v129
	v_add_f32_e32 v14, v126, v127
	v_add_f32_e32 v15, v130, v131
	v_add_f32_e32 v12, v12, v14
	v_add_f32_e32 v13, v13, v15
	v_add_f32_e32 v12, v12, v13
	s_nop 1
	v_add_f32_dpp v12, v12, v12 row_ror:8 row_mask:0xf bank_mask:0xf
	s_nop 1
	v_add_f32_dpp v12, v12, v12 row_ror:4 row_mask:0xf bank_mask:0xf
	s_nop 1
	v_add_f32_dpp v12, v12, v12 row_ror:2 row_mask:0xf bank_mask:0xf
	s_nop 1
	v_add_f32_dpp v12, v12, v12 row_ror:1 row_mask:0xf bank_mask:0xf
	v_fmac_f32_e32 v124, 0xbc000000, v12
	v_fmac_f32_e32 v125, 0xbc000000, v12
	v_fmac_f32_e32 v126, 0xbc000000, v12
	v_fmac_f32_e32 v127, 0xbc000000, v12
	v_fmac_f32_e32 v128, 0xbc000000, v12
	v_fmac_f32_e32 v129, 0xbc000000, v12
	v_fmac_f32_e32 v130, 0xbc000000, v12
	v_fmac_f32_e32 v131, 0xbc000000, v12
	v_mul_f32_e32 v13, v125, v125
	v_mul_f32_e32 v14, v129, v129
	v_mul_f32_e32 v15, v127, v127
	v_mul_f32_e32 v16, v131, v131
	v_fma_f32 v13, v124, v124, v13
	v_fma_f32 v14, v128, v128, v14
	v_fma_f32 v15, v126, v126, v15
	v_fma_f32 v16, v130, v130, v16
	v_add_f32_e32 v13, v13, v15
	v_add_f32_e32 v14, v14, v16
	v_add_f32_e32 v13, v13, v14
	s_nop 1
	v_add_f32_dpp v13, v13, v13 row_ror:8 row_mask:0xf bank_mask:0xf
	s_nop 1
	v_add_f32_dpp v13, v13, v13 row_ror:4 row_mask:0xf bank_mask:0xf
	s_nop 1
	v_add_f32_dpp v13, v13, v13 row_ror:2 row_mask:0xf bank_mask:0xf
	s_nop 1
	v_add_f32_dpp v13, v13, v13 row_ror:1 row_mask:0xf bank_mask:0xf
	v_lshlrev_b32_e32 v20, 16, v140
	v_and_b32_e32 v21, 0xffff0000, v140
	v_lshlrev_b32_e32 v22, 16, v141
	v_and_b32_e32 v23, 0xffff0000, v141
	v_lshlrev_b32_e32 v24, 16, v142
	v_and_b32_e32 v25, 0xffff0000, v142
	v_lshlrev_b32_e32 v26, 16, v143
	v_and_b32_e32 v27, 0xffff0000, v143
	v_mul_f32_e32 v28, 0xbfb8aa3b, v20
	v_mul_f32_e32 v29, 0xbfb8aa3b, v21
	v_mul_f32_e32 v30, 0xbfb8aa3b, v22
	v_mul_f32_e32 v31, 0xbfb8aa3b, v23
	v_mul_f32_e32 v32, 0xbfb8aa3b, v24
	v_mul_f32_e32 v33, 0xbfb8aa3b, v25
	v_mul_f32_e32 v34, 0xbfb8aa3b, v26
	v_mul_f32_e32 v35, 0xbfb8aa3b, v27
	v_exp_f32_e32 v28, v28
	v_exp_f32_e32 v29, v29
	v_exp_f32_e32 v30, v30
	v_exp_f32_e32 v31, v31
	v_exp_f32_e32 v32, v32
	v_exp_f32_e32 v33, v33
	v_exp_f32_e32 v34, v34
	v_exp_f32_e32 v35, v35
	v_fmamk_f32 v13, v13, 0x3c000000, v238
	v_cmp_gt_f32_e32 vcc, s67, v13
	v_mul_f32_e32 v14, 0x4b800000, v13
	s_nop 0
	v_cndmask_b32_e32 v13, v13, v14, vcc
	v_rsq_f32_e32 v13, v13
	v_add_f32_e32 v28, 1.0, v28
	v_add_f32_e32 v29, 1.0, v29
	v_add_f32_e32 v30, 1.0, v30
	v_add_f32_e32 v31, 1.0, v31
	v_add_f32_e32 v32, 1.0, v32
	v_add_f32_e32 v33, 1.0, v33
	v_add_f32_e32 v34, 1.0, v34
	v_add_f32_e32 v35, 1.0, v35
	v_rcp_f32_e32 v28, v28
	v_rcp_f32_e32 v29, v29
	v_rcp_f32_e32 v30, v30
	v_rcp_f32_e32 v31, v31
	v_rcp_f32_e32 v32, v32
	v_rcp_f32_e32 v33, v33
	v_rcp_f32_e32 v34, v34
	v_rcp_f32_e32 v35, v35
	v_mul_f32_e32 v14, 0x45800000, v13
	s_nop 0
	v_cndmask_b32_e32 v36, v13, v14, vcc
	v_pk_mul_f32 v[20:21], v[28:29], v[20:21]
	v_pk_mul_f32 v[22:23], v[30:31], v[22:23]
	v_pk_mul_f32 v[24:25], v[32:33], v[24:25]
	v_pk_mul_f32 v[26:27], v[34:35], v[26:27]
	v_pk_mul_f32 v[124:125], v[124:125], v[36:37] op_sel_hi:[1,0]
	v_pk_mul_f32 v[126:127], v[126:127], v[36:37] op_sel_hi:[1,0]
	v_pk_mul_f32 v[128:129], v[128:129], v[36:37] op_sel_hi:[1,0]
	v_pk_mul_f32 v[130:131], v[130:131], v[36:37] op_sel_hi:[1,0]
	v_pk_mul_f32 v[124:125], v[6:7], v[124:125]
	v_pk_mul_f32 v[126:127], v[8:9], v[126:127]
	v_pk_mul_f32 v[128:129], v[2:3], v[128:129]
	v_pk_mul_f32 v[130:131], v[4:5], v[130:131]
	v_pk_mul_f32 v[124:125], v[20:21], v[124:125]
	v_pk_mul_f32 v[126:127], v[22:23], v[126:127]
	v_pk_mul_f32 v[128:129], v[24:25], v[128:129]
	v_pk_mul_f32 v[130:131], v[26:27], v[130:131]
	v_cvt_pk_bf16_f32 v16, v124, v125
	v_cvt_pk_bf16_f32 v17, v126, v127
	v_cvt_pk_bf16_f32 v18, v128, v129
	v_cvt_pk_bf16_f32 v19, v130, v131
	v_add_u32_e32 v43, 0x4000, v42
	global_store_dwordx4 v43, v[16:19], s[10:11]
	s_waitcnt vmcnt(15)
	v_pk_add_f32 v[144:145], v[144:145], v[152:153]
	v_pk_add_f32 v[146:147], v[146:147], v[154:155]
	v_pk_add_f32 v[148:149], v[148:149], v[156:157]
	v_pk_add_f32 v[150:151], v[150:151], v[158:159]
	v_add_f32_e32 v12, v144, v145
	v_add_f32_e32 v13, v148, v149
	v_add_f32_e32 v14, v146, v147
	v_add_f32_e32 v15, v150, v151
	v_add_f32_e32 v12, v12, v14
	v_add_f32_e32 v13, v13, v15
	v_add_f32_e32 v12, v12, v13
	s_nop 1
	v_add_f32_dpp v12, v12, v12 row_ror:8 row_mask:0xf bank_mask:0xf
	s_nop 1
	v_add_f32_dpp v12, v12, v12 row_ror:4 row_mask:0xf bank_mask:0xf
	s_nop 1
	v_add_f32_dpp v12, v12, v12 row_ror:2 row_mask:0xf bank_mask:0xf
	s_nop 1
	v_add_f32_dpp v12, v12, v12 row_ror:1 row_mask:0xf bank_mask:0xf
	v_fmac_f32_e32 v144, 0xbc000000, v12
	v_fmac_f32_e32 v145, 0xbc000000, v12
	v_fmac_f32_e32 v146, 0xbc000000, v12
	v_fmac_f32_e32 v147, 0xbc000000, v12
	v_fmac_f32_e32 v148, 0xbc000000, v12
	v_fmac_f32_e32 v149, 0xbc000000, v12
	v_fmac_f32_e32 v150, 0xbc000000, v12
	v_fmac_f32_e32 v151, 0xbc000000, v12
	v_mul_f32_e32 v13, v145, v145
	v_mul_f32_e32 v14, v149, v149
	v_mul_f32_e32 v15, v147, v147
	v_mul_f32_e32 v16, v151, v151
	v_fma_f32 v13, v144, v144, v13
	v_fma_f32 v14, v148, v148, v14
	v_fma_f32 v15, v146, v146, v15
	v_fma_f32 v16, v150, v150, v16
	v_add_f32_e32 v13, v13, v15
	v_add_f32_e32 v14, v14, v16
	v_add_f32_e32 v13, v13, v14
	s_nop 1
	v_add_f32_dpp v13, v13, v13 row_ror:8 row_mask:0xf bank_mask:0xf
	s_nop 1
	v_add_f32_dpp v13, v13, v13 row_ror:4 row_mask:0xf bank_mask:0xf
	s_nop 1
	v_add_f32_dpp v13, v13, v13 row_ror:2 row_mask:0xf bank_mask:0xf
	s_nop 1
	v_add_f32_dpp v13, v13, v13 row_ror:1 row_mask:0xf bank_mask:0xf
	v_lshlrev_b32_e32 v20, 16, v160
	v_and_b32_e32 v21, 0xffff0000, v160
	v_lshlrev_b32_e32 v22, 16, v161
	v_and_b32_e32 v23, 0xffff0000, v161
	v_lshlrev_b32_e32 v24, 16, v162
	v_and_b32_e32 v25, 0xffff0000, v162
	v_lshlrev_b32_e32 v26, 16, v163
	v_and_b32_e32 v27, 0xffff0000, v163
	v_mul_f32_e32 v28, 0xbfb8aa3b, v20
	v_mul_f32_e32 v29, 0xbfb8aa3b, v21
	v_mul_f32_e32 v30, 0xbfb8aa3b, v22
	v_mul_f32_e32 v31, 0xbfb8aa3b, v23
	v_mul_f32_e32 v32, 0xbfb8aa3b, v24
	v_mul_f32_e32 v33, 0xbfb8aa3b, v25
	v_mul_f32_e32 v34, 0xbfb8aa3b, v26
	v_mul_f32_e32 v35, 0xbfb8aa3b, v27
	v_exp_f32_e32 v28, v28
	v_exp_f32_e32 v29, v29
	v_exp_f32_e32 v30, v30
	v_exp_f32_e32 v31, v31
	v_exp_f32_e32 v32, v32
	v_exp_f32_e32 v33, v33
	v_exp_f32_e32 v34, v34
	v_exp_f32_e32 v35, v35
	v_fmamk_f32 v13, v13, 0x3c000000, v238
	v_cmp_gt_f32_e32 vcc, s67, v13
	v_mul_f32_e32 v14, 0x4b800000, v13
	s_nop 0
	v_cndmask_b32_e32 v13, v13, v14, vcc
	v_rsq_f32_e32 v13, v13
	v_add_f32_e32 v28, 1.0, v28
	v_add_f32_e32 v29, 1.0, v29
	v_add_f32_e32 v30, 1.0, v30
	v_add_f32_e32 v31, 1.0, v31
	v_add_f32_e32 v32, 1.0, v32
	v_add_f32_e32 v33, 1.0, v33
	v_add_f32_e32 v34, 1.0, v34
	v_add_f32_e32 v35, 1.0, v35
	v_rcp_f32_e32 v28, v28
	v_rcp_f32_e32 v29, v29
	v_rcp_f32_e32 v30, v30
	v_rcp_f32_e32 v31, v31
	v_rcp_f32_e32 v32, v32
	v_rcp_f32_e32 v33, v33
	v_rcp_f32_e32 v34, v34
	v_rcp_f32_e32 v35, v35
	v_mul_f32_e32 v14, 0x45800000, v13
	s_nop 0
	v_cndmask_b32_e32 v36, v13, v14, vcc
	v_pk_mul_f32 v[20:21], v[28:29], v[20:21]
	v_pk_mul_f32 v[22:23], v[30:31], v[22:23]
	v_pk_mul_f32 v[24:25], v[32:33], v[24:25]
	v_pk_mul_f32 v[26:27], v[34:35], v[26:27]
	v_pk_mul_f32 v[144:145], v[144:145], v[36:37] op_sel_hi:[1,0]
	v_pk_mul_f32 v[146:147], v[146:147], v[36:37] op_sel_hi:[1,0]
	v_pk_mul_f32 v[148:149], v[148:149], v[36:37] op_sel_hi:[1,0]
	v_pk_mul_f32 v[150:151], v[150:151], v[36:37] op_sel_hi:[1,0]
	v_pk_mul_f32 v[144:145], v[6:7], v[144:145]
	v_pk_mul_f32 v[146:147], v[8:9], v[146:147]
	v_pk_mul_f32 v[148:149], v[2:3], v[148:149]
	v_pk_mul_f32 v[150:151], v[4:5], v[150:151]
	v_pk_mul_f32 v[144:145], v[20:21], v[144:145]
	v_pk_mul_f32 v[146:147], v[22:23], v[146:147]
	v_pk_mul_f32 v[148:149], v[24:25], v[148:149]
	v_pk_mul_f32 v[150:151], v[26:27], v[150:151]
	v_cvt_pk_bf16_f32 v16, v144, v145
	v_cvt_pk_bf16_f32 v17, v146, v147
	v_cvt_pk_bf16_f32 v18, v148, v149
	v_cvt_pk_bf16_f32 v19, v150, v151
	v_add_u32_e32 v43, 0x5000, v42
	global_store_dwordx4 v43, v[16:19], s[10:11]
	s_waitcnt vmcnt(11)
	v_pk_add_f32 v[164:165], v[164:165], v[172:173]
	v_pk_add_f32 v[166:167], v[166:167], v[174:175]
	v_pk_add_f32 v[168:169], v[168:169], v[176:177]
	v_pk_add_f32 v[170:171], v[170:171], v[178:179]
	v_add_f32_e32 v12, v164, v165
	v_add_f32_e32 v13, v168, v169
	v_add_f32_e32 v14, v166, v167
	v_add_f32_e32 v15, v170, v171
	v_add_f32_e32 v12, v12, v14
	v_add_f32_e32 v13, v13, v15
	v_add_f32_e32 v12, v12, v13
	s_nop 1
	v_add_f32_dpp v12, v12, v12 row_ror:8 row_mask:0xf bank_mask:0xf
	s_nop 1
	v_add_f32_dpp v12, v12, v12 row_ror:4 row_mask:0xf bank_mask:0xf
	s_nop 1
	v_add_f32_dpp v12, v12, v12 row_ror:2 row_mask:0xf bank_mask:0xf
	s_nop 1
	v_add_f32_dpp v12, v12, v12 row_ror:1 row_mask:0xf bank_mask:0xf
	v_fmac_f32_e32 v164, 0xbc000000, v12
	v_fmac_f32_e32 v165, 0xbc000000, v12
	v_fmac_f32_e32 v166, 0xbc000000, v12
	v_fmac_f32_e32 v167, 0xbc000000, v12
	v_fmac_f32_e32 v168, 0xbc000000, v12
	v_fmac_f32_e32 v169, 0xbc000000, v12
	v_fmac_f32_e32 v170, 0xbc000000, v12
	v_fmac_f32_e32 v171, 0xbc000000, v12
	v_mul_f32_e32 v13, v165, v165
	v_mul_f32_e32 v14, v169, v169
	v_mul_f32_e32 v15, v167, v167
	v_mul_f32_e32 v16, v171, v171
	v_fma_f32 v13, v164, v164, v13
	v_fma_f32 v14, v168, v168, v14
	v_fma_f32 v15, v166, v166, v15
	v_fma_f32 v16, v170, v170, v16
	v_add_f32_e32 v13, v13, v15
	v_add_f32_e32 v14, v14, v16
	v_add_f32_e32 v13, v13, v14
	s_nop 1
	v_add_f32_dpp v13, v13, v13 row_ror:8 row_mask:0xf bank_mask:0xf
	s_nop 1
	v_add_f32_dpp v13, v13, v13 row_ror:4 row_mask:0xf bank_mask:0xf
	s_nop 1
	v_add_f32_dpp v13, v13, v13 row_ror:2 row_mask:0xf bank_mask:0xf
	s_nop 1
	v_add_f32_dpp v13, v13, v13 row_ror:1 row_mask:0xf bank_mask:0xf
	v_lshlrev_b32_e32 v20, 16, v180
	v_and_b32_e32 v21, 0xffff0000, v180
	v_lshlrev_b32_e32 v22, 16, v181
	v_and_b32_e32 v23, 0xffff0000, v181
	v_lshlrev_b32_e32 v24, 16, v182
	v_and_b32_e32 v25, 0xffff0000, v182
	v_lshlrev_b32_e32 v26, 16, v183
	v_and_b32_e32 v27, 0xffff0000, v183
	v_mul_f32_e32 v28, 0xbfb8aa3b, v20
	v_mul_f32_e32 v29, 0xbfb8aa3b, v21
	v_mul_f32_e32 v30, 0xbfb8aa3b, v22
	v_mul_f32_e32 v31, 0xbfb8aa3b, v23
	v_mul_f32_e32 v32, 0xbfb8aa3b, v24
	v_mul_f32_e32 v33, 0xbfb8aa3b, v25
	v_mul_f32_e32 v34, 0xbfb8aa3b, v26
	v_mul_f32_e32 v35, 0xbfb8aa3b, v27
	v_exp_f32_e32 v28, v28
	v_exp_f32_e32 v29, v29
	v_exp_f32_e32 v30, v30
	v_exp_f32_e32 v31, v31
	v_exp_f32_e32 v32, v32
	v_exp_f32_e32 v33, v33
	v_exp_f32_e32 v34, v34
	v_exp_f32_e32 v35, v35
	v_fmamk_f32 v13, v13, 0x3c000000, v238
	v_cmp_gt_f32_e32 vcc, s67, v13
	v_mul_f32_e32 v14, 0x4b800000, v13
	s_nop 0
	v_cndmask_b32_e32 v13, v13, v14, vcc
	v_rsq_f32_e32 v13, v13
	v_add_f32_e32 v28, 1.0, v28
	v_add_f32_e32 v29, 1.0, v29
	v_add_f32_e32 v30, 1.0, v30
	v_add_f32_e32 v31, 1.0, v31
	v_add_f32_e32 v32, 1.0, v32
	v_add_f32_e32 v33, 1.0, v33
	v_add_f32_e32 v34, 1.0, v34
	v_add_f32_e32 v35, 1.0, v35
	v_rcp_f32_e32 v28, v28
	v_rcp_f32_e32 v29, v29
	v_rcp_f32_e32 v30, v30
	v_rcp_f32_e32 v31, v31
	v_rcp_f32_e32 v32, v32
	v_rcp_f32_e32 v33, v33
	v_rcp_f32_e32 v34, v34
	v_rcp_f32_e32 v35, v35
	v_mul_f32_e32 v14, 0x45800000, v13
	s_nop 0
	v_cndmask_b32_e32 v36, v13, v14, vcc
	v_pk_mul_f32 v[20:21], v[28:29], v[20:21]
	v_pk_mul_f32 v[22:23], v[30:31], v[22:23]
	v_pk_mul_f32 v[24:25], v[32:33], v[24:25]
	v_pk_mul_f32 v[26:27], v[34:35], v[26:27]
	v_pk_mul_f32 v[164:165], v[164:165], v[36:37] op_sel_hi:[1,0]
	v_pk_mul_f32 v[166:167], v[166:167], v[36:37] op_sel_hi:[1,0]
	v_pk_mul_f32 v[168:169], v[168:169], v[36:37] op_sel_hi:[1,0]
	v_pk_mul_f32 v[170:171], v[170:171], v[36:37] op_sel_hi:[1,0]
	v_pk_mul_f32 v[164:165], v[6:7], v[164:165]
	v_pk_mul_f32 v[166:167], v[8:9], v[166:167]
	v_pk_mul_f32 v[168:169], v[2:3], v[168:169]
	v_pk_mul_f32 v[170:171], v[4:5], v[170:171]
	v_pk_mul_f32 v[164:165], v[20:21], v[164:165]
	v_pk_mul_f32 v[166:167], v[22:23], v[166:167]
	v_pk_mul_f32 v[168:169], v[24:25], v[168:169]
	v_pk_mul_f32 v[170:171], v[26:27], v[170:171]
	v_cvt_pk_bf16_f32 v16, v164, v165
	v_cvt_pk_bf16_f32 v17, v166, v167
	v_cvt_pk_bf16_f32 v18, v168, v169
	v_cvt_pk_bf16_f32 v19, v170, v171
	v_add_u32_e32 v43, 0x6000, v42
	global_store_dwordx4 v43, v[16:19], s[10:11]
	s_waitcnt vmcnt(7)
	v_pk_add_f32 v[184:185], v[184:185], v[192:193]
	v_pk_add_f32 v[186:187], v[186:187], v[194:195]
	v_pk_add_f32 v[188:189], v[188:189], v[202:203]
	v_pk_add_f32 v[190:191], v[190:191], v[204:205]
	v_add_f32_e32 v12, v184, v185
	v_add_f32_e32 v13, v188, v189
	v_add_f32_e32 v14, v186, v187
	v_add_f32_e32 v15, v190, v191
	v_add_f32_e32 v12, v12, v14
	v_add_f32_e32 v13, v13, v15
	v_add_f32_e32 v12, v12, v13
	s_nop 1
	v_add_f32_dpp v12, v12, v12 row_ror:8 row_mask:0xf bank_mask:0xf
	s_nop 1
	v_add_f32_dpp v12, v12, v12 row_ror:4 row_mask:0xf bank_mask:0xf
	s_nop 1
	v_add_f32_dpp v12, v12, v12 row_ror:2 row_mask:0xf bank_mask:0xf
	s_nop 1
	v_add_f32_dpp v12, v12, v12 row_ror:1 row_mask:0xf bank_mask:0xf
	v_fmac_f32_e32 v184, 0xbc000000, v12
	v_fmac_f32_e32 v185, 0xbc000000, v12
	v_fmac_f32_e32 v186, 0xbc000000, v12
	v_fmac_f32_e32 v187, 0xbc000000, v12
	v_fmac_f32_e32 v188, 0xbc000000, v12
	v_fmac_f32_e32 v189, 0xbc000000, v12
	v_fmac_f32_e32 v190, 0xbc000000, v12
	v_fmac_f32_e32 v191, 0xbc000000, v12
	v_mul_f32_e32 v13, v185, v185
	v_mul_f32_e32 v14, v189, v189
	v_mul_f32_e32 v15, v187, v187
	v_mul_f32_e32 v16, v191, v191
	v_fma_f32 v13, v184, v184, v13
	v_fma_f32 v14, v188, v188, v14
	v_fma_f32 v15, v186, v186, v15
	v_fma_f32 v16, v190, v190, v16
	v_add_f32_e32 v13, v13, v15
	v_add_f32_e32 v14, v14, v16
	v_add_f32_e32 v13, v13, v14
	s_nop 1
	v_add_f32_dpp v13, v13, v13 row_ror:8 row_mask:0xf bank_mask:0xf
	s_nop 1
	v_add_f32_dpp v13, v13, v13 row_ror:4 row_mask:0xf bank_mask:0xf
	s_nop 1
	v_add_f32_dpp v13, v13, v13 row_ror:2 row_mask:0xf bank_mask:0xf
	s_nop 1
	v_add_f32_dpp v13, v13, v13 row_ror:1 row_mask:0xf bank_mask:0xf
	v_lshlrev_b32_e32 v20, 16, v206
	v_and_b32_e32 v21, 0xffff0000, v206
	v_lshlrev_b32_e32 v22, 16, v207
	v_and_b32_e32 v23, 0xffff0000, v207
	v_lshlrev_b32_e32 v24, 16, v208
	v_and_b32_e32 v25, 0xffff0000, v208
	v_lshlrev_b32_e32 v26, 16, v209
	v_and_b32_e32 v27, 0xffff0000, v209
	v_mul_f32_e32 v28, 0xbfb8aa3b, v20
	v_mul_f32_e32 v29, 0xbfb8aa3b, v21
	v_mul_f32_e32 v30, 0xbfb8aa3b, v22
	v_mul_f32_e32 v31, 0xbfb8aa3b, v23
	v_mul_f32_e32 v32, 0xbfb8aa3b, v24
	v_mul_f32_e32 v33, 0xbfb8aa3b, v25
	v_mul_f32_e32 v34, 0xbfb8aa3b, v26
	v_mul_f32_e32 v35, 0xbfb8aa3b, v27
	v_exp_f32_e32 v28, v28
	v_exp_f32_e32 v29, v29
	v_exp_f32_e32 v30, v30
	v_exp_f32_e32 v31, v31
	v_exp_f32_e32 v32, v32
	v_exp_f32_e32 v33, v33
	v_exp_f32_e32 v34, v34
	v_exp_f32_e32 v35, v35
	v_fmamk_f32 v13, v13, 0x3c000000, v238
	v_cmp_gt_f32_e32 vcc, s67, v13
	v_mul_f32_e32 v14, 0x4b800000, v13
	s_nop 0
	v_cndmask_b32_e32 v13, v13, v14, vcc
	v_rsq_f32_e32 v13, v13
	v_add_f32_e32 v28, 1.0, v28
	v_add_f32_e32 v29, 1.0, v29
	v_add_f32_e32 v30, 1.0, v30
	v_add_f32_e32 v31, 1.0, v31
	v_add_f32_e32 v32, 1.0, v32
	v_add_f32_e32 v33, 1.0, v33
	v_add_f32_e32 v34, 1.0, v34
	v_add_f32_e32 v35, 1.0, v35
	v_rcp_f32_e32 v28, v28
	v_rcp_f32_e32 v29, v29
	v_rcp_f32_e32 v30, v30
	v_rcp_f32_e32 v31, v31
	v_rcp_f32_e32 v32, v32
	v_rcp_f32_e32 v33, v33
	v_rcp_f32_e32 v34, v34
	v_rcp_f32_e32 v35, v35
	v_mul_f32_e32 v14, 0x45800000, v13
	s_nop 0
	v_cndmask_b32_e32 v36, v13, v14, vcc
	v_pk_mul_f32 v[20:21], v[28:29], v[20:21]
	v_pk_mul_f32 v[22:23], v[30:31], v[22:23]
	v_pk_mul_f32 v[24:25], v[32:33], v[24:25]
	v_pk_mul_f32 v[26:27], v[34:35], v[26:27]
	v_pk_mul_f32 v[184:185], v[184:185], v[36:37] op_sel_hi:[1,0]
	v_pk_mul_f32 v[186:187], v[186:187], v[36:37] op_sel_hi:[1,0]
	v_pk_mul_f32 v[188:189], v[188:189], v[36:37] op_sel_hi:[1,0]
	v_pk_mul_f32 v[190:191], v[190:191], v[36:37] op_sel_hi:[1,0]
	v_pk_mul_f32 v[184:185], v[6:7], v[184:185]
	v_pk_mul_f32 v[186:187], v[8:9], v[186:187]
	v_pk_mul_f32 v[188:189], v[2:3], v[188:189]
	v_pk_mul_f32 v[190:191], v[4:5], v[190:191]
	v_pk_mul_f32 v[184:185], v[20:21], v[184:185]
	v_pk_mul_f32 v[186:187], v[22:23], v[186:187]
	v_pk_mul_f32 v[188:189], v[24:25], v[188:189]
	v_pk_mul_f32 v[190:191], v[26:27], v[190:191]
	v_cvt_pk_bf16_f32 v16, v184, v185
	v_cvt_pk_bf16_f32 v17, v186, v187
	v_cvt_pk_bf16_f32 v18, v188, v189
	v_cvt_pk_bf16_f32 v19, v190, v191
	v_add_u32_e32 v43, 0x7000, v42
	global_store_dwordx4 v43, v[16:19], s[10:11]
	s_mov_b64 s[0:1], 0

.LBB0_406:
	v_add_u32_e32 v12, 0x1000, v11
	v_lshlrev_b32_e32 v40, 11, v12
	v_lshl_add_u32 v40, v10, 2, v40
	v_mad_u32_u24 v41, v12, s66, v0
	v_lshlrev_b32_e32 v42, 10, v12
	v_lshl_add_u32 v42, v10, 1, v42
	s_add_u32 s0, s4, 0x823fa00
	s_addc_u32 s1, s5, 0
	s_add_u32 s0, s0, s64
	s_addc_u32 s1, s1, 0
	global_load_dwordx4 v[44:47], v40, s[6:7]
	global_load_dwordx4 v[48:51], v40, s[6:7] offset:16
	global_load_dwordx4 v[52:55], v40, s[8:9]
	global_load_dwordx4 v[56:59], v40, s[8:9] offset:16
	global_load_dwordx4 v[60:63], v41, s[0:1]
	v_add_u32_e32 v43, 0x2000, v40
	global_load_dwordx4 v[64:67], v43, s[6:7]
	global_load_dwordx4 v[68:71], v43, s[6:7] offset:16
	global_load_dwordx4 v[72:75], v43, s[8:9]
	global_load_dwordx4 v[76:79], v43, s[8:9] offset:16
	v_add_u32_e32 v43, 0x7800, v41
	global_load_dwordx4 v[80:83], v43, s[0:1]
	v_add_u32_e32 v43, 0x4000, v40
	global_load_dwordx4 v[84:87], v43, s[6:7]
	global_load_dwordx4 v[88:91], v43, s[6:7] offset:16
	global_load_dwordx4 v[92:95], v43, s[8:9]
	global_load_dwordx4 v[96:99], v43, s[8:9] offset:16
	v_add_u32_e32 v43, 0xf000, v41
	global_load_dwordx4 v[100:103], v43, s[0:1]
	v_add_u32_e32 v43, 0x6000, v40
	global_load_dwordx4 v[104:107], v43, s[6:7]
	global_load_dwordx4 v[108:111], v43, s[6:7] offset:16
	global_load_dwordx4 v[112:115], v43, s[8:9]
	global_load_dwordx4 v[116:119], v43, s[8:9] offset:16
	v_add_u32_e32 v43, 0x16800, v41
	global_load_dwordx4 v[120:123], v43, s[0:1]
	v_add_u32_e32 v43, 0x8000, v40
	global_load_dwordx4 v[124:127], v43, s[6:7]
	global_load_dwordx4 v[128:131], v43, s[6:7] offset:16
	global_load_dwordx4 v[132:135], v43, s[8:9]
	global_load_dwordx4 v[136:139], v43, s[8:9] offset:16
	v_add_u32_e32 v43, 0x1e000, v41
	global_load_dwordx4 v[140:143], v43, s[0:1]
	v_add_u32_e32 v43, 0xa000, v40
	global_load_dwordx4 v[144:147], v43, s[6:7]
	global_load_dwordx4 v[148:151], v43, s[6:7] offset:16
	global_load_dwordx4 v[152:155], v43, s[8:9]
	global_load_dwordx4 v[156:159], v43, s[8:9] offset:16
	v_add_u32_e32 v43, 0x25800, v41
	global_load_dwordx4 v[160:163], v43, s[0:1]
	v_add_u32_e32 v43, 0xc000, v40
	global_load_dwordx4 v[164:167], v43, s[6:7]
	global_load_dwordx4 v[168:171], v43, s[6:7] offset:16
	global_load_dwordx4 v[172:175], v43, s[8:9]
	global_load_dwordx4 v[176:179], v43, s[8:9] offset:16
	v_add_u32_e32 v43, 0x2d000, v41
	global_load_dwordx4 v[180:183], v43, s[0:1]
	v_add_u32_e32 v43, 0xe000, v40
	global_load_dwordx4 v[184:187], v43, s[6:7]
	global_load_dwordx4 v[188:191], v43, s[6:7] offset:16
	global_load_dwordx4 v[192:195], v43, s[8:9]
	global_load_dwordx4 v[202:205], v43, s[8:9] offset:16
	v_add_u32_e32 v43, 0x34800, v41
	global_load_dwordx4 v[206:209], v43, s[0:1]
	s_waitcnt vmcnt(35)
	v_pk_add_f32 v[44:45], v[44:45], v[52:53]
	v_pk_add_f32 v[46:47], v[46:47], v[54:55]
	v_pk_add_f32 v[48:49], v[48:49], v[56:57]
	v_pk_add_f32 v[50:51], v[50:51], v[58:59]
	v_add_f32_e32 v12, v44, v45
	v_add_f32_e32 v13, v48, v49
	v_add_f32_e32 v14, v46, v47
	v_add_f32_e32 v15, v50, v51
	v_add_f32_e32 v12, v12, v14
	v_add_f32_e32 v13, v13, v15
	v_add_f32_e32 v12, v12, v13
	s_nop 1
	v_add_f32_dpp v12, v12, v12 row_ror:8 row_mask:0xf bank_mask:0xf
	s_nop 1
	v_add_f32_dpp v12, v12, v12 row_ror:4 row_mask:0xf bank_mask:0xf
	s_nop 1
	v_add_f32_dpp v12, v12, v12 row_ror:2 row_mask:0xf bank_mask:0xf
	s_nop 1
	v_add_f32_dpp v12, v12, v12 row_ror:1 row_mask:0xf bank_mask:0xf
	v_fmac_f32_e32 v44, 0xbc000000, v12
	v_fmac_f32_e32 v45, 0xbc000000, v12
	v_fmac_f32_e32 v46, 0xbc000000, v12
	v_fmac_f32_e32 v47, 0xbc000000, v12
	v_fmac_f32_e32 v48, 0xbc000000, v12
	v_fmac_f32_e32 v49, 0xbc000000, v12
	v_fmac_f32_e32 v50, 0xbc000000, v12
	v_fmac_f32_e32 v51, 0xbc000000, v12
	v_mul_f32_e32 v13, v45, v45
	v_mul_f32_e32 v14, v49, v49
	v_mul_f32_e32 v15, v47, v47
	v_mul_f32_e32 v16, v51, v51
	v_fma_f32 v13, v44, v44, v13
	v_fma_f32 v14, v48, v48, v14
	v_fma_f32 v15, v46, v46, v15
	v_fma_f32 v16, v50, v50, v16
	v_add_f32_e32 v13, v13, v15
	v_add_f32_e32 v14, v14, v16
	v_add_f32_e32 v13, v13, v14
	s_nop 1
	v_add_f32_dpp v13, v13, v13 row_ror:8 row_mask:0xf bank_mask:0xf
	s_nop 1
	v_add_f32_dpp v13, v13, v13 row_ror:4 row_mask:0xf bank_mask:0xf
	s_nop 1
	v_add_f32_dpp v13, v13, v13 row_ror:2 row_mask:0xf bank_mask:0xf
	s_nop 1
	v_add_f32_dpp v13, v13, v13 row_ror:1 row_mask:0xf bank_mask:0xf
	v_lshlrev_b32_e32 v20, 16, v60
	v_and_b32_e32 v21, 0xffff0000, v60
	v_lshlrev_b32_e32 v22, 16, v61
	v_and_b32_e32 v23, 0xffff0000, v61
	v_lshlrev_b32_e32 v24, 16, v62
	v_and_b32_e32 v25, 0xffff0000, v62
	v_lshlrev_b32_e32 v26, 16, v63
	v_and_b32_e32 v27, 0xffff0000, v63
	v_mul_f32_e32 v28, 0xbfb8aa3b, v20
	v_mul_f32_e32 v29, 0xbfb8aa3b, v21
	v_mul_f32_e32 v30, 0xbfb8aa3b, v22
	v_mul_f32_e32 v31, 0xbfb8aa3b, v23
	v_mul_f32_e32 v32, 0xbfb8aa3b, v24
	v_mul_f32_e32 v33, 0xbfb8aa3b, v25
	v_mul_f32_e32 v34, 0xbfb8aa3b, v26
	v_mul_f32_e32 v35, 0xbfb8aa3b, v27
	v_exp_f32_e32 v28, v28
	v_exp_f32_e32 v29, v29
	v_exp_f32_e32 v30, v30
	v_exp_f32_e32 v31, v31
	v_exp_f32_e32 v32, v32
	v_exp_f32_e32 v33, v33
	v_exp_f32_e32 v34, v34
	v_exp_f32_e32 v35, v35
	v_fmamk_f32 v13, v13, 0x3c000000, v238
	v_cmp_gt_f32_e32 vcc, s67, v13
	v_mul_f32_e32 v14, 0x4b800000, v13
	s_nop 0
	v_cndmask_b32_e32 v13, v13, v14, vcc
	v_rsq_f32_e32 v13, v13
	v_add_f32_e32 v28, 1.0, v28
	v_add_f32_e32 v29, 1.0, v29
	v_add_f32_e32 v30, 1.0, v30
	v_add_f32_e32 v31, 1.0, v31
	v_add_f32_e32 v32, 1.0, v32
	v_add_f32_e32 v33, 1.0, v33
	v_add_f32_e32 v34, 1.0, v34
	v_add_f32_e32 v35, 1.0, v35
	v_rcp_f32_e32 v28, v28
	v_rcp_f32_e32 v29, v29
	v_rcp_f32_e32 v30, v30
	v_rcp_f32_e32 v31, v31
	v_rcp_f32_e32 v32, v32
	v_rcp_f32_e32 v33, v33
	v_rcp_f32_e32 v34, v34
	v_rcp_f32_e32 v35, v35
	v_mul_f32_e32 v14, 0x45800000, v13
	s_nop 0
	v_cndmask_b32_e32 v36, v13, v14, vcc
	v_pk_mul_f32 v[20:21], v[28:29], v[20:21]
	v_pk_mul_f32 v[22:23], v[30:31], v[22:23]
	v_pk_mul_f32 v[24:25], v[32:33], v[24:25]
	v_pk_mul_f32 v[26:27], v[34:35], v[26:27]
	v_pk_mul_f32 v[44:45], v[44:45], v[36:37] op_sel_hi:[1,0]
	v_pk_mul_f32 v[46:47], v[46:47], v[36:37] op_sel_hi:[1,0]
	v_pk_mul_f32 v[48:49], v[48:49], v[36:37] op_sel_hi:[1,0]
	v_pk_mul_f32 v[50:51], v[50:51], v[36:37] op_sel_hi:[1,0]
	v_pk_mul_f32 v[44:45], v[6:7], v[44:45]
	v_pk_mul_f32 v[46:47], v[8:9], v[46:47]
	v_pk_mul_f32 v[48:49], v[2:3], v[48:49]
	v_pk_mul_f32 v[50:51], v[4:5], v[50:51]
	v_pk_mul_f32 v[44:45], v[20:21], v[44:45]
	v_pk_mul_f32 v[46:47], v[22:23], v[46:47]
	v_pk_mul_f32 v[48:49], v[24:25], v[48:49]
	v_pk_mul_f32 v[50:51], v[26:27], v[50:51]
	v_cvt_pk_bf16_f32 v16, v44, v45
	v_cvt_pk_bf16_f32 v17, v46, v47
	v_cvt_pk_bf16_f32 v18, v48, v49
	v_cvt_pk_bf16_f32 v19, v50, v51
	global_store_dwordx4 v42, v[16:19], s[10:11]
	s_waitcnt vmcnt(31)
	v_pk_add_f32 v[64:65], v[64:65], v[72:73]
	v_pk_add_f32 v[66:67], v[66:67], v[74:75]
	v_pk_add_f32 v[68:69], v[68:69], v[76:77]
	v_pk_add_f32 v[70:71], v[70:71], v[78:79]
	v_add_f32_e32 v12, v64, v65
	v_add_f32_e32 v13, v68, v69
	v_add_f32_e32 v14, v66, v67
	v_add_f32_e32 v15, v70, v71
	v_add_f32_e32 v12, v12, v14
	v_add_f32_e32 v13, v13, v15
	v_add_f32_e32 v12, v12, v13
	s_nop 1
	v_add_f32_dpp v12, v12, v12 row_ror:8 row_mask:0xf bank_mask:0xf
	s_nop 1
	v_add_f32_dpp v12, v12, v12 row_ror:4 row_mask:0xf bank_mask:0xf
	s_nop 1
	v_add_f32_dpp v12, v12, v12 row_ror:2 row_mask:0xf bank_mask:0xf
	s_nop 1
	v_add_f32_dpp v12, v12, v12 row_ror:1 row_mask:0xf bank_mask:0xf
	v_fmac_f32_e32 v64, 0xbc000000, v12
	v_fmac_f32_e32 v65, 0xbc000000, v12
	v_fmac_f32_e32 v66, 0xbc000000, v12
	v_fmac_f32_e32 v67, 0xbc000000, v12
	v_fmac_f32_e32 v68, 0xbc000000, v12
	v_fmac_f32_e32 v69, 0xbc000000, v12
	v_fmac_f32_e32 v70, 0xbc000000, v12
	v_fmac_f32_e32 v71, 0xbc000000, v12
	v_mul_f32_e32 v13, v65, v65
	v_mul_f32_e32 v14, v69, v69
	v_mul_f32_e32 v15, v67, v67
	v_mul_f32_e32 v16, v71, v71
	v_fma_f32 v13, v64, v64, v13
	v_fma_f32 v14, v68, v68, v14
	v_fma_f32 v15, v66, v66, v15
	v_fma_f32 v16, v70, v70, v16
	v_add_f32_e32 v13, v13, v15
	v_add_f32_e32 v14, v14, v16
	v_add_f32_e32 v13, v13, v14
	s_nop 1
	v_add_f32_dpp v13, v13, v13 row_ror:8 row_mask:0xf bank_mask:0xf
	s_nop 1
	v_add_f32_dpp v13, v13, v13 row_ror:4 row_mask:0xf bank_mask:0xf
	s_nop 1
	v_add_f32_dpp v13, v13, v13 row_ror:2 row_mask:0xf bank_mask:0xf
	s_nop 1
	v_add_f32_dpp v13, v13, v13 row_ror:1 row_mask:0xf bank_mask:0xf
	v_lshlrev_b32_e32 v20, 16, v80
	v_and_b32_e32 v21, 0xffff0000, v80
	v_lshlrev_b32_e32 v22, 16, v81
	v_and_b32_e32 v23, 0xffff0000, v81
	v_lshlrev_b32_e32 v24, 16, v82
	v_and_b32_e32 v25, 0xffff0000, v82
	v_lshlrev_b32_e32 v26, 16, v83
	v_and_b32_e32 v27, 0xffff0000, v83
	v_mul_f32_e32 v28, 0xbfb8aa3b, v20
	v_mul_f32_e32 v29, 0xbfb8aa3b, v21
	v_mul_f32_e32 v30, 0xbfb8aa3b, v22
	v_mul_f32_e32 v31, 0xbfb8aa3b, v23
	v_mul_f32_e32 v32, 0xbfb8aa3b, v24
	v_mul_f32_e32 v33, 0xbfb8aa3b, v25
	v_mul_f32_e32 v34, 0xbfb8aa3b, v26
	v_mul_f32_e32 v35, 0xbfb8aa3b, v27
	v_exp_f32_e32 v28, v28
	v_exp_f32_e32 v29, v29
	v_exp_f32_e32 v30, v30
	v_exp_f32_e32 v31, v31
	v_exp_f32_e32 v32, v32
	v_exp_f32_e32 v33, v33
	v_exp_f32_e32 v34, v34
	v_exp_f32_e32 v35, v35
	v_fmamk_f32 v13, v13, 0x3c000000, v238
	v_cmp_gt_f32_e32 vcc, s67, v13
	v_mul_f32_e32 v14, 0x4b800000, v13
	s_nop 0
	v_cndmask_b32_e32 v13, v13, v14, vcc
	v_rsq_f32_e32 v13, v13
	v_add_f32_e32 v28, 1.0, v28
	v_add_f32_e32 v29, 1.0, v29
	v_add_f32_e32 v30, 1.0, v30
	v_add_f32_e32 v31, 1.0, v31
	v_add_f32_e32 v32, 1.0, v32
	v_add_f32_e32 v33, 1.0, v33
	v_add_f32_e32 v34, 1.0, v34
	v_add_f32_e32 v35, 1.0, v35
	v_rcp_f32_e32 v28, v28
	v_rcp_f32_e32 v29, v29
	v_rcp_f32_e32 v30, v30
	v_rcp_f32_e32 v31, v31
	v_rcp_f32_e32 v32, v32
	v_rcp_f32_e32 v33, v33
	v_rcp_f32_e32 v34, v34
	v_rcp_f32_e32 v35, v35
	v_mul_f32_e32 v14, 0x45800000, v13
	s_nop 0
	v_cndmask_b32_e32 v36, v13, v14, vcc
	v_pk_mul_f32 v[20:21], v[28:29], v[20:21]
	v_pk_mul_f32 v[22:23], v[30:31], v[22:23]
	v_pk_mul_f32 v[24:25], v[32:33], v[24:25]
	v_pk_mul_f32 v[26:27], v[34:35], v[26:27]
	v_pk_mul_f32 v[64:65], v[64:65], v[36:37] op_sel_hi:[1,0]
	v_pk_mul_f32 v[66:67], v[66:67], v[36:37] op_sel_hi:[1,0]
	v_pk_mul_f32 v[68:69], v[68:69], v[36:37] op_sel_hi:[1,0]
	v_pk_mul_f32 v[70:71], v[70:71], v[36:37] op_sel_hi:[1,0]
	v_pk_mul_f32 v[64:65], v[6:7], v[64:65]
	v_pk_mul_f32 v[66:67], v[8:9], v[66:67]
	v_pk_mul_f32 v[68:69], v[2:3], v[68:69]
	v_pk_mul_f32 v[70:71], v[4:5], v[70:71]
	v_pk_mul_f32 v[64:65], v[20:21], v[64:65]
	v_pk_mul_f32 v[66:67], v[22:23], v[66:67]
	v_pk_mul_f32 v[68:69], v[24:25], v[68:69]
	v_pk_mul_f32 v[70:71], v[26:27], v[70:71]
	v_cvt_pk_bf16_f32 v16, v64, v65
	v_cvt_pk_bf16_f32 v17, v66, v67
	v_cvt_pk_bf16_f32 v18, v68, v69
	v_cvt_pk_bf16_f32 v19, v70, v71
	v_add_u32_e32 v43, 0x1000, v42
	global_store_dwordx4 v43, v[16:19], s[10:11]
	s_waitcnt vmcnt(27)
	v_pk_add_f32 v[84:85], v[84:85], v[92:93]
	v_pk_add_f32 v[86:87], v[86:87], v[94:95]
	v_pk_add_f32 v[88:89], v[88:89], v[96:97]
	v_pk_add_f32 v[90:91], v[90:91], v[98:99]
	v_add_f32_e32 v12, v84, v85
	v_add_f32_e32 v13, v88, v89
	v_add_f32_e32 v14, v86, v87
	v_add_f32_e32 v15, v90, v91
	v_add_f32_e32 v12, v12, v14
	v_add_f32_e32 v13, v13, v15
	v_add_f32_e32 v12, v12, v13
	s_nop 1
	v_add_f32_dpp v12, v12, v12 row_ror:8 row_mask:0xf bank_mask:0xf
	s_nop 1
	v_add_f32_dpp v12, v12, v12 row_ror:4 row_mask:0xf bank_mask:0xf
	s_nop 1
	v_add_f32_dpp v12, v12, v12 row_ror:2 row_mask:0xf bank_mask:0xf
	s_nop 1
	v_add_f32_dpp v12, v12, v12 row_ror:1 row_mask:0xf bank_mask:0xf
	v_fmac_f32_e32 v84, 0xbc000000, v12
	v_fmac_f32_e32 v85, 0xbc000000, v12
	v_fmac_f32_e32 v86, 0xbc000000, v12
	v_fmac_f32_e32 v87, 0xbc000000, v12
	v_fmac_f32_e32 v88, 0xbc000000, v12
	v_fmac_f32_e32 v89, 0xbc000000, v12
	v_fmac_f32_e32 v90, 0xbc000000, v12
	v_fmac_f32_e32 v91, 0xbc000000, v12
	v_mul_f32_e32 v13, v85, v85
	v_mul_f32_e32 v14, v89, v89
	v_mul_f32_e32 v15, v87, v87
	v_mul_f32_e32 v16, v91, v91
	v_fma_f32 v13, v84, v84, v13
	v_fma_f32 v14, v88, v88, v14
	v_fma_f32 v15, v86, v86, v15
	v_fma_f32 v16, v90, v90, v16
	v_add_f32_e32 v13, v13, v15
	v_add_f32_e32 v14, v14, v16
	v_add_f32_e32 v13, v13, v14
	s_nop 1
	v_add_f32_dpp v13, v13, v13 row_ror:8 row_mask:0xf bank_mask:0xf
	s_nop 1
	v_add_f32_dpp v13, v13, v13 row_ror:4 row_mask:0xf bank_mask:0xf
	s_nop 1
	v_add_f32_dpp v13, v13, v13 row_ror:2 row_mask:0xf bank_mask:0xf
	s_nop 1
	v_add_f32_dpp v13, v13, v13 row_ror:1 row_mask:0xf bank_mask:0xf
	v_lshlrev_b32_e32 v20, 16, v100
	v_and_b32_e32 v21, 0xffff0000, v100
	v_lshlrev_b32_e32 v22, 16, v101
	v_and_b32_e32 v23, 0xffff0000, v101
	v_lshlrev_b32_e32 v24, 16, v102
	v_and_b32_e32 v25, 0xffff0000, v102
	v_lshlrev_b32_e32 v26, 16, v103
	v_and_b32_e32 v27, 0xffff0000, v103
	v_mul_f32_e32 v28, 0xbfb8aa3b, v20
	v_mul_f32_e32 v29, 0xbfb8aa3b, v21
	v_mul_f32_e32 v30, 0xbfb8aa3b, v22
	v_mul_f32_e32 v31, 0xbfb8aa3b, v23
	v_mul_f32_e32 v32, 0xbfb8aa3b, v24
	v_mul_f32_e32 v33, 0xbfb8aa3b, v25
	v_mul_f32_e32 v34, 0xbfb8aa3b, v26
	v_mul_f32_e32 v35, 0xbfb8aa3b, v27
	v_exp_f32_e32 v28, v28
	v_exp_f32_e32 v29, v29
	v_exp_f32_e32 v30, v30
	v_exp_f32_e32 v31, v31
	v_exp_f32_e32 v32, v32
	v_exp_f32_e32 v33, v33
	v_exp_f32_e32 v34, v34
	v_exp_f32_e32 v35, v35
	v_fmamk_f32 v13, v13, 0x3c000000, v238
	v_cmp_gt_f32_e32 vcc, s67, v13
	v_mul_f32_e32 v14, 0x4b800000, v13
	s_nop 0
	v_cndmask_b32_e32 v13, v13, v14, vcc
	v_rsq_f32_e32 v13, v13
	v_add_f32_e32 v28, 1.0, v28
	v_add_f32_e32 v29, 1.0, v29
	v_add_f32_e32 v30, 1.0, v30
	v_add_f32_e32 v31, 1.0, v31
	v_add_f32_e32 v32, 1.0, v32
	v_add_f32_e32 v33, 1.0, v33
	v_add_f32_e32 v34, 1.0, v34
	v_add_f32_e32 v35, 1.0, v35
	v_rcp_f32_e32 v28, v28
	v_rcp_f32_e32 v29, v29
	v_rcp_f32_e32 v30, v30
	v_rcp_f32_e32 v31, v31
	v_rcp_f32_e32 v32, v32
	v_rcp_f32_e32 v33, v33
	v_rcp_f32_e32 v34, v34
	v_rcp_f32_e32 v35, v35
	v_mul_f32_e32 v14, 0x45800000, v13
	s_nop 0
	v_cndmask_b32_e32 v36, v13, v14, vcc
	v_pk_mul_f32 v[20:21], v[28:29], v[20:21]
	v_pk_mul_f32 v[22:23], v[30:31], v[22:23]
	v_pk_mul_f32 v[24:25], v[32:33], v[24:25]
	v_pk_mul_f32 v[26:27], v[34:35], v[26:27]
	v_pk_mul_f32 v[84:85], v[84:85], v[36:37] op_sel_hi:[1,0]
	v_pk_mul_f32 v[86:87], v[86:87], v[36:37] op_sel_hi:[1,0]
	v_pk_mul_f32 v[88:89], v[88:89], v[36:37] op_sel_hi:[1,0]
	v_pk_mul_f32 v[90:91], v[90:91], v[36:37] op_sel_hi:[1,0]
	v_pk_mul_f32 v[84:85], v[6:7], v[84:85]
	v_pk_mul_f32 v[86:87], v[8:9], v[86:87]
	v_pk_mul_f32 v[88:89], v[2:3], v[88:89]
	v_pk_mul_f32 v[90:91], v[4:5], v[90:91]
	v_pk_mul_f32 v[84:85], v[20:21], v[84:85]
	v_pk_mul_f32 v[86:87], v[22:23], v[86:87]
	v_pk_mul_f32 v[88:89], v[24:25], v[88:89]
	v_pk_mul_f32 v[90:91], v[26:27], v[90:91]
	v_cvt_pk_bf16_f32 v16, v84, v85
	v_cvt_pk_bf16_f32 v17, v86, v87
	v_cvt_pk_bf16_f32 v18, v88, v89
	v_cvt_pk_bf16_f32 v19, v90, v91
	v_add_u32_e32 v43, 0x2000, v42
	global_store_dwordx4 v43, v[16:19], s[10:11]
	s_waitcnt vmcnt(23)
	v_pk_add_f32 v[104:105], v[104:105], v[112:113]
	v_pk_add_f32 v[106:107], v[106:107], v[114:115]
	v_pk_add_f32 v[108:109], v[108:109], v[116:117]
	v_pk_add_f32 v[110:111], v[110:111], v[118:119]
	v_add_f32_e32 v12, v104, v105
	v_add_f32_e32 v13, v108, v109
	v_add_f32_e32 v14, v106, v107
	v_add_f32_e32 v15, v110, v111
	v_add_f32_e32 v12, v12, v14
	v_add_f32_e32 v13, v13, v15
	v_add_f32_e32 v12, v12, v13
	s_nop 1
	v_add_f32_dpp v12, v12, v12 row_ror:8 row_mask:0xf bank_mask:0xf
	s_nop 1
	v_add_f32_dpp v12, v12, v12 row_ror:4 row_mask:0xf bank_mask:0xf
	s_nop 1
	v_add_f32_dpp v12, v12, v12 row_ror:2 row_mask:0xf bank_mask:0xf
	s_nop 1
	v_add_f32_dpp v12, v12, v12 row_ror:1 row_mask:0xf bank_mask:0xf
	v_fmac_f32_e32 v104, 0xbc000000, v12
	v_fmac_f32_e32 v105, 0xbc000000, v12
	v_fmac_f32_e32 v106, 0xbc000000, v12
	v_fmac_f32_e32 v107, 0xbc000000, v12
	v_fmac_f32_e32 v108, 0xbc000000, v12
	v_fmac_f32_e32 v109, 0xbc000000, v12
	v_fmac_f32_e32 v110, 0xbc000000, v12
	v_fmac_f32_e32 v111, 0xbc000000, v12
	v_mul_f32_e32 v13, v105, v105
	v_mul_f32_e32 v14, v109, v109
	v_mul_f32_e32 v15, v107, v107
	v_mul_f32_e32 v16, v111, v111
	v_fma_f32 v13, v104, v104, v13
	v_fma_f32 v14, v108, v108, v14
	v_fma_f32 v15, v106, v106, v15
	v_fma_f32 v16, v110, v110, v16
	v_add_f32_e32 v13, v13, v15
	v_add_f32_e32 v14, v14, v16
	v_add_f32_e32 v13, v13, v14
	s_nop 1
	v_add_f32_dpp v13, v13, v13 row_ror:8 row_mask:0xf bank_mask:0xf
	s_nop 1
	v_add_f32_dpp v13, v13, v13 row_ror:4 row_mask:0xf bank_mask:0xf
	s_nop 1
	v_add_f32_dpp v13, v13, v13 row_ror:2 row_mask:0xf bank_mask:0xf
	s_nop 1
	v_add_f32_dpp v13, v13, v13 row_ror:1 row_mask:0xf bank_mask:0xf
	v_lshlrev_b32_e32 v20, 16, v120
	v_and_b32_e32 v21, 0xffff0000, v120
	v_lshlrev_b32_e32 v22, 16, v121
	v_and_b32_e32 v23, 0xffff0000, v121
	v_lshlrev_b32_e32 v24, 16, v122
	v_and_b32_e32 v25, 0xffff0000, v122
	v_lshlrev_b32_e32 v26, 16, v123
	v_and_b32_e32 v27, 0xffff0000, v123
	v_mul_f32_e32 v28, 0xbfb8aa3b, v20
	v_mul_f32_e32 v29, 0xbfb8aa3b, v21
	v_mul_f32_e32 v30, 0xbfb8aa3b, v22
	v_mul_f32_e32 v31, 0xbfb8aa3b, v23
	v_mul_f32_e32 v32, 0xbfb8aa3b, v24
	v_mul_f32_e32 v33, 0xbfb8aa3b, v25
	v_mul_f32_e32 v34, 0xbfb8aa3b, v26
	v_mul_f32_e32 v35, 0xbfb8aa3b, v27
	v_exp_f32_e32 v28, v28
	v_exp_f32_e32 v29, v29
	v_exp_f32_e32 v30, v30
	v_exp_f32_e32 v31, v31
	v_exp_f32_e32 v32, v32
	v_exp_f32_e32 v33, v33
	v_exp_f32_e32 v34, v34
	v_exp_f32_e32 v35, v35
	v_fmamk_f32 v13, v13, 0x3c000000, v238
	v_cmp_gt_f32_e32 vcc, s67, v13
	v_mul_f32_e32 v14, 0x4b800000, v13
	s_nop 0
	v_cndmask_b32_e32 v13, v13, v14, vcc
	v_rsq_f32_e32 v13, v13
	v_add_f32_e32 v28, 1.0, v28
	v_add_f32_e32 v29, 1.0, v29
	v_add_f32_e32 v30, 1.0, v30
	v_add_f32_e32 v31, 1.0, v31
	v_add_f32_e32 v32, 1.0, v32
	v_add_f32_e32 v33, 1.0, v33
	v_add_f32_e32 v34, 1.0, v34
	v_add_f32_e32 v35, 1.0, v35
	v_rcp_f32_e32 v28, v28
	v_rcp_f32_e32 v29, v29
	v_rcp_f32_e32 v30, v30
	v_rcp_f32_e32 v31, v31
	v_rcp_f32_e32 v32, v32
	v_rcp_f32_e32 v33, v33
	v_rcp_f32_e32 v34, v34
	v_rcp_f32_e32 v35, v35
	v_mul_f32_e32 v14, 0x45800000, v13
	s_nop 0
	v_cndmask_b32_e32 v36, v13, v14, vcc
	v_pk_mul_f32 v[20:21], v[28:29], v[20:21]
	v_pk_mul_f32 v[22:23], v[30:31], v[22:23]
	v_pk_mul_f32 v[24:25], v[32:33], v[24:25]
	v_pk_mul_f32 v[26:27], v[34:35], v[26:27]
	v_pk_mul_f32 v[104:105], v[104:105], v[36:37] op_sel_hi:[1,0]
	v_pk_mul_f32 v[106:107], v[106:107], v[36:37] op_sel_hi:[1,0]
	v_pk_mul_f32 v[108:109], v[108:109], v[36:37] op_sel_hi:[1,0]
	v_pk_mul_f32 v[110:111], v[110:111], v[36:37] op_sel_hi:[1,0]
	v_pk_mul_f32 v[104:105], v[6:7], v[104:105]
	v_pk_mul_f32 v[106:107], v[8:9], v[106:107]
	v_pk_mul_f32 v[108:109], v[2:3], v[108:109]
	v_pk_mul_f32 v[110:111], v[4:5], v[110:111]
	v_pk_mul_f32 v[104:105], v[20:21], v[104:105]
	v_pk_mul_f32 v[106:107], v[22:23], v[106:107]
	v_pk_mul_f32 v[108:109], v[24:25], v[108:109]
	v_pk_mul_f32 v[110:111], v[26:27], v[110:111]
	v_cvt_pk_bf16_f32 v16, v104, v105
	v_cvt_pk_bf16_f32 v17, v106, v107
	v_cvt_pk_bf16_f32 v18, v108, v109
	v_cvt_pk_bf16_f32 v19, v110, v111
	v_add_u32_e32 v43, 0x3000, v42
	global_store_dwordx4 v43, v[16:19], s[10:11]
	s_waitcnt vmcnt(19)
	v_pk_add_f32 v[124:125], v[124:125], v[132:133]
	v_pk_add_f32 v[126:127], v[126:127], v[134:135]
	v_pk_add_f32 v[128:129], v[128:129], v[136:137]
	v_pk_add_f32 v[130:131], v[130:131], v[138:139]
	v_add_f32_e32 v12, v124, v125
	v_add_f32_e32 v13, v128, v129
	v_add_f32_e32 v14, v126, v127
	v_add_f32_e32 v15, v130, v131
	v_add_f32_e32 v12, v12, v14
	v_add_f32_e32 v13, v13, v15
	v_add_f32_e32 v12, v12, v13
	s_nop 1
	v_add_f32_dpp v12, v12, v12 row_ror:8 row_mask:0xf bank_mask:0xf
	s_nop 1
	v_add_f32_dpp v12, v12, v12 row_ror:4 row_mask:0xf bank_mask:0xf
	s_nop 1
	v_add_f32_dpp v12, v12, v12 row_ror:2 row_mask:0xf bank_mask:0xf
	s_nop 1
	v_add_f32_dpp v12, v12, v12 row_ror:1 row_mask:0xf bank_mask:0xf
	v_fmac_f32_e32 v124, 0xbc000000, v12
	v_fmac_f32_e32 v125, 0xbc000000, v12
	v_fmac_f32_e32 v126, 0xbc000000, v12
	v_fmac_f32_e32 v127, 0xbc000000, v12
	v_fmac_f32_e32 v128, 0xbc000000, v12
	v_fmac_f32_e32 v129, 0xbc000000, v12
	v_fmac_f32_e32 v130, 0xbc000000, v12
	v_fmac_f32_e32 v131, 0xbc000000, v12
	v_mul_f32_e32 v13, v125, v125
	v_mul_f32_e32 v14, v129, v129
	v_mul_f32_e32 v15, v127, v127
	v_mul_f32_e32 v16, v131, v131
	v_fma_f32 v13, v124, v124, v13
	v_fma_f32 v14, v128, v128, v14
	v_fma_f32 v15, v126, v126, v15
	v_fma_f32 v16, v130, v130, v16
	v_add_f32_e32 v13, v13, v15
	v_add_f32_e32 v14, v14, v16
	v_add_f32_e32 v13, v13, v14
	s_nop 1
	v_add_f32_dpp v13, v13, v13 row_ror:8 row_mask:0xf bank_mask:0xf
	s_nop 1
	v_add_f32_dpp v13, v13, v13 row_ror:4 row_mask:0xf bank_mask:0xf
	s_nop 1
	v_add_f32_dpp v13, v13, v13 row_ror:2 row_mask:0xf bank_mask:0xf
	s_nop 1
	v_add_f32_dpp v13, v13, v13 row_ror:1 row_mask:0xf bank_mask:0xf
	v_lshlrev_b32_e32 v20, 16, v140
	v_and_b32_e32 v21, 0xffff0000, v140
	v_lshlrev_b32_e32 v22, 16, v141
	v_and_b32_e32 v23, 0xffff0000, v141
	v_lshlrev_b32_e32 v24, 16, v142
	v_and_b32_e32 v25, 0xffff0000, v142
	v_lshlrev_b32_e32 v26, 16, v143
	v_and_b32_e32 v27, 0xffff0000, v143
	v_mul_f32_e32 v28, 0xbfb8aa3b, v20
	v_mul_f32_e32 v29, 0xbfb8aa3b, v21
	v_mul_f32_e32 v30, 0xbfb8aa3b, v22
	v_mul_f32_e32 v31, 0xbfb8aa3b, v23
	v_mul_f32_e32 v32, 0xbfb8aa3b, v24
	v_mul_f32_e32 v33, 0xbfb8aa3b, v25
	v_mul_f32_e32 v34, 0xbfb8aa3b, v26
	v_mul_f32_e32 v35, 0xbfb8aa3b, v27
	v_exp_f32_e32 v28, v28
	v_exp_f32_e32 v29, v29
	v_exp_f32_e32 v30, v30
	v_exp_f32_e32 v31, v31
	v_exp_f32_e32 v32, v32
	v_exp_f32_e32 v33, v33
	v_exp_f32_e32 v34, v34
	v_exp_f32_e32 v35, v35
	v_fmamk_f32 v13, v13, 0x3c000000, v238
	v_cmp_gt_f32_e32 vcc, s67, v13
	v_mul_f32_e32 v14, 0x4b800000, v13
	s_nop 0
	v_cndmask_b32_e32 v13, v13, v14, vcc
	v_rsq_f32_e32 v13, v13
	v_add_f32_e32 v28, 1.0, v28
	v_add_f32_e32 v29, 1.0, v29
	v_add_f32_e32 v30, 1.0, v30
	v_add_f32_e32 v31, 1.0, v31
	v_add_f32_e32 v32, 1.0, v32
	v_add_f32_e32 v33, 1.0, v33
	v_add_f32_e32 v34, 1.0, v34
	v_add_f32_e32 v35, 1.0, v35
	v_rcp_f32_e32 v28, v28
	v_rcp_f32_e32 v29, v29
	v_rcp_f32_e32 v30, v30
	v_rcp_f32_e32 v31, v31
	v_rcp_f32_e32 v32, v32
	v_rcp_f32_e32 v33, v33
	v_rcp_f32_e32 v34, v34
	v_rcp_f32_e32 v35, v35
	v_mul_f32_e32 v14, 0x45800000, v13
	s_nop 0
	v_cndmask_b32_e32 v36, v13, v14, vcc
	v_pk_mul_f32 v[20:21], v[28:29], v[20:21]
	v_pk_mul_f32 v[22:23], v[30:31], v[22:23]
	v_pk_mul_f32 v[24:25], v[32:33], v[24:25]
	v_pk_mul_f32 v[26:27], v[34:35], v[26:27]
	v_pk_mul_f32 v[124:125], v[124:125], v[36:37] op_sel_hi:[1,0]
	v_pk_mul_f32 v[126:127], v[126:127], v[36:37] op_sel_hi:[1,0]
	v_pk_mul_f32 v[128:129], v[128:129], v[36:37] op_sel_hi:[1,0]
	v_pk_mul_f32 v[130:131], v[130:131], v[36:37] op_sel_hi:[1,0]
	v_pk_mul_f32 v[124:125], v[6:7], v[124:125]
	v_pk_mul_f32 v[126:127], v[8:9], v[126:127]
	v_pk_mul_f32 v[128:129], v[2:3], v[128:129]
	v_pk_mul_f32 v[130:131], v[4:5], v[130:131]
	v_pk_mul_f32 v[124:125], v[20:21], v[124:125]
	v_pk_mul_f32 v[126:127], v[22:23], v[126:127]
	v_pk_mul_f32 v[128:129], v[24:25], v[128:129]
	v_pk_mul_f32 v[130:131], v[26:27], v[130:131]
	v_cvt_pk_bf16_f32 v16, v124, v125
	v_cvt_pk_bf16_f32 v17, v126, v127
	v_cvt_pk_bf16_f32 v18, v128, v129
	v_cvt_pk_bf16_f32 v19, v130, v131
	v_add_u32_e32 v43, 0x4000, v42
	global_store_dwordx4 v43, v[16:19], s[10:11]
	s_waitcnt vmcnt(15)
	v_pk_add_f32 v[144:145], v[144:145], v[152:153]
	v_pk_add_f32 v[146:147], v[146:147], v[154:155]
	v_pk_add_f32 v[148:149], v[148:149], v[156:157]
	v_pk_add_f32 v[150:151], v[150:151], v[158:159]
	v_add_f32_e32 v12, v144, v145
	v_add_f32_e32 v13, v148, v149
	v_add_f32_e32 v14, v146, v147
	v_add_f32_e32 v15, v150, v151
	v_add_f32_e32 v12, v12, v14
	v_add_f32_e32 v13, v13, v15
	v_add_f32_e32 v12, v12, v13
	s_nop 1
	v_add_f32_dpp v12, v12, v12 row_ror:8 row_mask:0xf bank_mask:0xf
	s_nop 1
	v_add_f32_dpp v12, v12, v12 row_ror:4 row_mask:0xf bank_mask:0xf
	s_nop 1
	v_add_f32_dpp v12, v12, v12 row_ror:2 row_mask:0xf bank_mask:0xf
	s_nop 1
	v_add_f32_dpp v12, v12, v12 row_ror:1 row_mask:0xf bank_mask:0xf
	v_fmac_f32_e32 v144, 0xbc000000, v12
	v_fmac_f32_e32 v145, 0xbc000000, v12
	v_fmac_f32_e32 v146, 0xbc000000, v12
	v_fmac_f32_e32 v147, 0xbc000000, v12
	v_fmac_f32_e32 v148, 0xbc000000, v12
	v_fmac_f32_e32 v149, 0xbc000000, v12
	v_fmac_f32_e32 v150, 0xbc000000, v12
	v_fmac_f32_e32 v151, 0xbc000000, v12
	v_mul_f32_e32 v13, v145, v145
	v_mul_f32_e32 v14, v149, v149
	v_mul_f32_e32 v15, v147, v147
	v_mul_f32_e32 v16, v151, v151
	v_fma_f32 v13, v144, v144, v13
	v_fma_f32 v14, v148, v148, v14
	v_fma_f32 v15, v146, v146, v15
	v_fma_f32 v16, v150, v150, v16
	v_add_f32_e32 v13, v13, v15
	v_add_f32_e32 v14, v14, v16
	v_add_f32_e32 v13, v13, v14
	s_nop 1
	v_add_f32_dpp v13, v13, v13 row_ror:8 row_mask:0xf bank_mask:0xf
	s_nop 1
	v_add_f32_dpp v13, v13, v13 row_ror:4 row_mask:0xf bank_mask:0xf
	s_nop 1
	v_add_f32_dpp v13, v13, v13 row_ror:2 row_mask:0xf bank_mask:0xf
	s_nop 1
	v_add_f32_dpp v13, v13, v13 row_ror:1 row_mask:0xf bank_mask:0xf
	v_lshlrev_b32_e32 v20, 16, v160
	v_and_b32_e32 v21, 0xffff0000, v160
	v_lshlrev_b32_e32 v22, 16, v161
	v_and_b32_e32 v23, 0xffff0000, v161
	v_lshlrev_b32_e32 v24, 16, v162
	v_and_b32_e32 v25, 0xffff0000, v162
	v_lshlrev_b32_e32 v26, 16, v163
	v_and_b32_e32 v27, 0xffff0000, v163
	v_mul_f32_e32 v28, 0xbfb8aa3b, v20
	v_mul_f32_e32 v29, 0xbfb8aa3b, v21
	v_mul_f32_e32 v30, 0xbfb8aa3b, v22
	v_mul_f32_e32 v31, 0xbfb8aa3b, v23
	v_mul_f32_e32 v32, 0xbfb8aa3b, v24
	v_mul_f32_e32 v33, 0xbfb8aa3b, v25
	v_mul_f32_e32 v34, 0xbfb8aa3b, v26
	v_mul_f32_e32 v35, 0xbfb8aa3b, v27
	v_exp_f32_e32 v28, v28
	v_exp_f32_e32 v29, v29
	v_exp_f32_e32 v30, v30
	v_exp_f32_e32 v31, v31
	v_exp_f32_e32 v32, v32
	v_exp_f32_e32 v33, v33
	v_exp_f32_e32 v34, v34
	v_exp_f32_e32 v35, v35
	v_fmamk_f32 v13, v13, 0x3c000000, v238
	v_cmp_gt_f32_e32 vcc, s67, v13
	v_mul_f32_e32 v14, 0x4b800000, v13
	s_nop 0
	v_cndmask_b32_e32 v13, v13, v14, vcc
	v_rsq_f32_e32 v13, v13
	v_add_f32_e32 v28, 1.0, v28
	v_add_f32_e32 v29, 1.0, v29
	v_add_f32_e32 v30, 1.0, v30
	v_add_f32_e32 v31, 1.0, v31
	v_add_f32_e32 v32, 1.0, v32
	v_add_f32_e32 v33, 1.0, v33
	v_add_f32_e32 v34, 1.0, v34
	v_add_f32_e32 v35, 1.0, v35
	v_rcp_f32_e32 v28, v28
	v_rcp_f32_e32 v29, v29
	v_rcp_f32_e32 v30, v30
	v_rcp_f32_e32 v31, v31
	v_rcp_f32_e32 v32, v32
	v_rcp_f32_e32 v33, v33
	v_rcp_f32_e32 v34, v34
	v_rcp_f32_e32 v35, v35
	v_mul_f32_e32 v14, 0x45800000, v13
	s_nop 0
	v_cndmask_b32_e32 v36, v13, v14, vcc
	v_pk_mul_f32 v[20:21], v[28:29], v[20:21]
	v_pk_mul_f32 v[22:23], v[30:31], v[22:23]
	v_pk_mul_f32 v[24:25], v[32:33], v[24:25]
	v_pk_mul_f32 v[26:27], v[34:35], v[26:27]
	v_pk_mul_f32 v[144:145], v[144:145], v[36:37] op_sel_hi:[1,0]
	v_pk_mul_f32 v[146:147], v[146:147], v[36:37] op_sel_hi:[1,0]
	v_pk_mul_f32 v[148:149], v[148:149], v[36:37] op_sel_hi:[1,0]
	v_pk_mul_f32 v[150:151], v[150:151], v[36:37] op_sel_hi:[1,0]
	v_pk_mul_f32 v[144:145], v[6:7], v[144:145]
	v_pk_mul_f32 v[146:147], v[8:9], v[146:147]
	v_pk_mul_f32 v[148:149], v[2:3], v[148:149]
	v_pk_mul_f32 v[150:151], v[4:5], v[150:151]
	v_pk_mul_f32 v[144:145], v[20:21], v[144:145]
	v_pk_mul_f32 v[146:147], v[22:23], v[146:147]
	v_pk_mul_f32 v[148:149], v[24:25], v[148:149]
	v_pk_mul_f32 v[150:151], v[26:27], v[150:151]
	v_cvt_pk_bf16_f32 v16, v144, v145
	v_cvt_pk_bf16_f32 v17, v146, v147
	v_cvt_pk_bf16_f32 v18, v148, v149
	v_cvt_pk_bf16_f32 v19, v150, v151
	v_add_u32_e32 v43, 0x5000, v42
	global_store_dwordx4 v43, v[16:19], s[10:11]
	s_waitcnt vmcnt(11)
	v_pk_add_f32 v[164:165], v[164:165], v[172:173]
	v_pk_add_f32 v[166:167], v[166:167], v[174:175]
	v_pk_add_f32 v[168:169], v[168:169], v[176:177]
	v_pk_add_f32 v[170:171], v[170:171], v[178:179]
	v_add_f32_e32 v12, v164, v165
	v_add_f32_e32 v13, v168, v169
	v_add_f32_e32 v14, v166, v167
	v_add_f32_e32 v15, v170, v171
	v_add_f32_e32 v12, v12, v14
	v_add_f32_e32 v13, v13, v15
	v_add_f32_e32 v12, v12, v13
	s_nop 1
	v_add_f32_dpp v12, v12, v12 row_ror:8 row_mask:0xf bank_mask:0xf
	s_nop 1
	v_add_f32_dpp v12, v12, v12 row_ror:4 row_mask:0xf bank_mask:0xf
	s_nop 1
	v_add_f32_dpp v12, v12, v12 row_ror:2 row_mask:0xf bank_mask:0xf
	s_nop 1
	v_add_f32_dpp v12, v12, v12 row_ror:1 row_mask:0xf bank_mask:0xf
	v_fmac_f32_e32 v164, 0xbc000000, v12
	v_fmac_f32_e32 v165, 0xbc000000, v12
	v_fmac_f32_e32 v166, 0xbc000000, v12
	v_fmac_f32_e32 v167, 0xbc000000, v12
	v_fmac_f32_e32 v168, 0xbc000000, v12
	v_fmac_f32_e32 v169, 0xbc000000, v12
	v_fmac_f32_e32 v170, 0xbc000000, v12
	v_fmac_f32_e32 v171, 0xbc000000, v12
	v_mul_f32_e32 v13, v165, v165
	v_mul_f32_e32 v14, v169, v169
	v_mul_f32_e32 v15, v167, v167
	v_mul_f32_e32 v16, v171, v171
	v_fma_f32 v13, v164, v164, v13
	v_fma_f32 v14, v168, v168, v14
	v_fma_f32 v15, v166, v166, v15
	v_fma_f32 v16, v170, v170, v16
	v_add_f32_e32 v13, v13, v15
	v_add_f32_e32 v14, v14, v16
	v_add_f32_e32 v13, v13, v14
	s_nop 1
	v_add_f32_dpp v13, v13, v13 row_ror:8 row_mask:0xf bank_mask:0xf
	s_nop 1
	v_add_f32_dpp v13, v13, v13 row_ror:4 row_mask:0xf bank_mask:0xf
	s_nop 1
	v_add_f32_dpp v13, v13, v13 row_ror:2 row_mask:0xf bank_mask:0xf
	s_nop 1
	v_add_f32_dpp v13, v13, v13 row_ror:1 row_mask:0xf bank_mask:0xf
	v_lshlrev_b32_e32 v20, 16, v180
	v_and_b32_e32 v21, 0xffff0000, v180
	v_lshlrev_b32_e32 v22, 16, v181
	v_and_b32_e32 v23, 0xffff0000, v181
	v_lshlrev_b32_e32 v24, 16, v182
	v_and_b32_e32 v25, 0xffff0000, v182
	v_lshlrev_b32_e32 v26, 16, v183
	v_and_b32_e32 v27, 0xffff0000, v183
	v_mul_f32_e32 v28, 0xbfb8aa3b, v20
	v_mul_f32_e32 v29, 0xbfb8aa3b, v21
	v_mul_f32_e32 v30, 0xbfb8aa3b, v22
	v_mul_f32_e32 v31, 0xbfb8aa3b, v23
	v_mul_f32_e32 v32, 0xbfb8aa3b, v24
	v_mul_f32_e32 v33, 0xbfb8aa3b, v25
	v_mul_f32_e32 v34, 0xbfb8aa3b, v26
	v_mul_f32_e32 v35, 0xbfb8aa3b, v27
	v_exp_f32_e32 v28, v28
	v_exp_f32_e32 v29, v29
	v_exp_f32_e32 v30, v30
	v_exp_f32_e32 v31, v31
	v_exp_f32_e32 v32, v32
	v_exp_f32_e32 v33, v33
	v_exp_f32_e32 v34, v34
	v_exp_f32_e32 v35, v35
	v_fmamk_f32 v13, v13, 0x3c000000, v238
	v_cmp_gt_f32_e32 vcc, s67, v13
	v_mul_f32_e32 v14, 0x4b800000, v13
	s_nop 0
	v_cndmask_b32_e32 v13, v13, v14, vcc
	v_rsq_f32_e32 v13, v13
	v_add_f32_e32 v28, 1.0, v28
	v_add_f32_e32 v29, 1.0, v29
	v_add_f32_e32 v30, 1.0, v30
	v_add_f32_e32 v31, 1.0, v31
	v_add_f32_e32 v32, 1.0, v32
	v_add_f32_e32 v33, 1.0, v33
	v_add_f32_e32 v34, 1.0, v34
	v_add_f32_e32 v35, 1.0, v35
	v_rcp_f32_e32 v28, v28
	v_rcp_f32_e32 v29, v29
	v_rcp_f32_e32 v30, v30
	v_rcp_f32_e32 v31, v31
	v_rcp_f32_e32 v32, v32
	v_rcp_f32_e32 v33, v33
	v_rcp_f32_e32 v34, v34
	v_rcp_f32_e32 v35, v35
	v_mul_f32_e32 v14, 0x45800000, v13
	s_nop 0
	v_cndmask_b32_e32 v36, v13, v14, vcc
	v_pk_mul_f32 v[20:21], v[28:29], v[20:21]
	v_pk_mul_f32 v[22:23], v[30:31], v[22:23]
	v_pk_mul_f32 v[24:25], v[32:33], v[24:25]
	v_pk_mul_f32 v[26:27], v[34:35], v[26:27]
	v_pk_mul_f32 v[164:165], v[164:165], v[36:37] op_sel_hi:[1,0]
	v_pk_mul_f32 v[166:167], v[166:167], v[36:37] op_sel_hi:[1,0]
	v_pk_mul_f32 v[168:169], v[168:169], v[36:37] op_sel_hi:[1,0]
	v_pk_mul_f32 v[170:171], v[170:171], v[36:37] op_sel_hi:[1,0]
	v_pk_mul_f32 v[164:165], v[6:7], v[164:165]
	v_pk_mul_f32 v[166:167], v[8:9], v[166:167]
	v_pk_mul_f32 v[168:169], v[2:3], v[168:169]
	v_pk_mul_f32 v[170:171], v[4:5], v[170:171]
	v_pk_mul_f32 v[164:165], v[20:21], v[164:165]
	v_pk_mul_f32 v[166:167], v[22:23], v[166:167]
	v_pk_mul_f32 v[168:169], v[24:25], v[168:169]
	v_pk_mul_f32 v[170:171], v[26:27], v[170:171]
	v_cvt_pk_bf16_f32 v16, v164, v165
	v_cvt_pk_bf16_f32 v17, v166, v167
	v_cvt_pk_bf16_f32 v18, v168, v169
	v_cvt_pk_bf16_f32 v19, v170, v171
	v_add_u32_e32 v43, 0x6000, v42
	global_store_dwordx4 v43, v[16:19], s[10:11]
	s_waitcnt vmcnt(7)
	v_pk_add_f32 v[184:185], v[184:185], v[192:193]
	v_pk_add_f32 v[186:187], v[186:187], v[194:195]
	v_pk_add_f32 v[188:189], v[188:189], v[202:203]
	v_pk_add_f32 v[190:191], v[190:191], v[204:205]
	v_add_f32_e32 v12, v184, v185
	v_add_f32_e32 v13, v188, v189
	v_add_f32_e32 v14, v186, v187
	v_add_f32_e32 v15, v190, v191
	v_add_f32_e32 v12, v12, v14
	v_add_f32_e32 v13, v13, v15
	v_add_f32_e32 v12, v12, v13
	s_nop 1
	v_add_f32_dpp v12, v12, v12 row_ror:8 row_mask:0xf bank_mask:0xf
	s_nop 1
	v_add_f32_dpp v12, v12, v12 row_ror:4 row_mask:0xf bank_mask:0xf
	s_nop 1
	v_add_f32_dpp v12, v12, v12 row_ror:2 row_mask:0xf bank_mask:0xf
	s_nop 1
	v_add_f32_dpp v12, v12, v12 row_ror:1 row_mask:0xf bank_mask:0xf
	v_fmac_f32_e32 v184, 0xbc000000, v12
	v_fmac_f32_e32 v185, 0xbc000000, v12
	v_fmac_f32_e32 v186, 0xbc000000, v12
	v_fmac_f32_e32 v187, 0xbc000000, v12
	v_fmac_f32_e32 v188, 0xbc000000, v12
	v_fmac_f32_e32 v189, 0xbc000000, v12
	v_fmac_f32_e32 v190, 0xbc000000, v12
	v_fmac_f32_e32 v191, 0xbc000000, v12
	v_mul_f32_e32 v13, v185, v185
	v_mul_f32_e32 v14, v189, v189
	v_mul_f32_e32 v15, v187, v187
	v_mul_f32_e32 v16, v191, v191
	v_fma_f32 v13, v184, v184, v13
	v_fma_f32 v14, v188, v188, v14
	v_fma_f32 v15, v186, v186, v15
	v_fma_f32 v16, v190, v190, v16
	v_add_f32_e32 v13, v13, v15
	v_add_f32_e32 v14, v14, v16
	v_add_f32_e32 v13, v13, v14
	s_nop 1
	v_add_f32_dpp v13, v13, v13 row_ror:8 row_mask:0xf bank_mask:0xf
	s_nop 1
	v_add_f32_dpp v13, v13, v13 row_ror:4 row_mask:0xf bank_mask:0xf
	s_nop 1
	v_add_f32_dpp v13, v13, v13 row_ror:2 row_mask:0xf bank_mask:0xf
	s_nop 1
	v_add_f32_dpp v13, v13, v13 row_ror:1 row_mask:0xf bank_mask:0xf
	v_lshlrev_b32_e32 v20, 16, v206
	v_and_b32_e32 v21, 0xffff0000, v206
	v_lshlrev_b32_e32 v22, 16, v207
	v_and_b32_e32 v23, 0xffff0000, v207
	v_lshlrev_b32_e32 v24, 16, v208
	v_and_b32_e32 v25, 0xffff0000, v208
	v_lshlrev_b32_e32 v26, 16, v209
	v_and_b32_e32 v27, 0xffff0000, v209
	v_mul_f32_e32 v28, 0xbfb8aa3b, v20
	v_mul_f32_e32 v29, 0xbfb8aa3b, v21
	v_mul_f32_e32 v30, 0xbfb8aa3b, v22
	v_mul_f32_e32 v31, 0xbfb8aa3b, v23
	v_mul_f32_e32 v32, 0xbfb8aa3b, v24
	v_mul_f32_e32 v33, 0xbfb8aa3b, v25
	v_mul_f32_e32 v34, 0xbfb8aa3b, v26
	v_mul_f32_e32 v35, 0xbfb8aa3b, v27
	v_exp_f32_e32 v28, v28
	v_exp_f32_e32 v29, v29
	v_exp_f32_e32 v30, v30
	v_exp_f32_e32 v31, v31
	v_exp_f32_e32 v32, v32
	v_exp_f32_e32 v33, v33
	v_exp_f32_e32 v34, v34
	v_exp_f32_e32 v35, v35
	v_fmamk_f32 v13, v13, 0x3c000000, v238
	v_cmp_gt_f32_e32 vcc, s67, v13
	v_mul_f32_e32 v14, 0x4b800000, v13
	s_nop 0
	v_cndmask_b32_e32 v13, v13, v14, vcc
	v_rsq_f32_e32 v13, v13
	v_add_f32_e32 v28, 1.0, v28
	v_add_f32_e32 v29, 1.0, v29
	v_add_f32_e32 v30, 1.0, v30
	v_add_f32_e32 v31, 1.0, v31
	v_add_f32_e32 v32, 1.0, v32
	v_add_f32_e32 v33, 1.0, v33
	v_add_f32_e32 v34, 1.0, v34
	v_add_f32_e32 v35, 1.0, v35
	v_rcp_f32_e32 v28, v28
	v_rcp_f32_e32 v29, v29
	v_rcp_f32_e32 v30, v30
	v_rcp_f32_e32 v31, v31
	v_rcp_f32_e32 v32, v32
	v_rcp_f32_e32 v33, v33
	v_rcp_f32_e32 v34, v34
	v_rcp_f32_e32 v35, v35
	v_mul_f32_e32 v14, 0x45800000, v13
	s_nop 0
	v_cndmask_b32_e32 v36, v13, v14, vcc
	v_pk_mul_f32 v[20:21], v[28:29], v[20:21]
	v_pk_mul_f32 v[22:23], v[30:31], v[22:23]
	v_pk_mul_f32 v[24:25], v[32:33], v[24:25]
	v_pk_mul_f32 v[26:27], v[34:35], v[26:27]
	v_pk_mul_f32 v[184:185], v[184:185], v[36:37] op_sel_hi:[1,0]
	v_pk_mul_f32 v[186:187], v[186:187], v[36:37] op_sel_hi:[1,0]
	v_pk_mul_f32 v[188:189], v[188:189], v[36:37] op_sel_hi:[1,0]
	v_pk_mul_f32 v[190:191], v[190:191], v[36:37] op_sel_hi:[1,0]
	v_pk_mul_f32 v[184:185], v[6:7], v[184:185]
	v_pk_mul_f32 v[186:187], v[8:9], v[186:187]
	v_pk_mul_f32 v[188:189], v[2:3], v[188:189]
	v_pk_mul_f32 v[190:191], v[4:5], v[190:191]
	v_pk_mul_f32 v[184:185], v[20:21], v[184:185]
	v_pk_mul_f32 v[186:187], v[22:23], v[186:187]
	v_pk_mul_f32 v[188:189], v[24:25], v[188:189]
	v_pk_mul_f32 v[190:191], v[26:27], v[190:191]
	v_cvt_pk_bf16_f32 v16, v184, v185
	v_cvt_pk_bf16_f32 v17, v186, v187
	v_cvt_pk_bf16_f32 v18, v188, v189
	v_cvt_pk_bf16_f32 v19, v190, v191
	v_add_u32_e32 v43, 0x7000, v42
	global_store_dwordx4 v43, v[16:19], s[10:11]

.LBB0_629:
	s_or_b64 exec, exec, s[0:1]
	s_lshl_b64 s[0:1], s[24:25], 17
	s_add_u32 s0, s22, s0
	s_addc_u32 s1, s23, s1
	v_readlane_b32 s36, v254, 28
	s_add_u32 s36, s0, 0x823e000
	v_readlane_b32 s37, v254, 29
	s_addc_u32 s0, s1, 0
	s_barrier
	s_and_b32 s37, s0, 0xffff
	s_mov_b32 s1, s71
	s_mov_b32 s0, 0
	v_readlane_b32 s28, v254, 24
	s_xor_b64 s[0:1], s[0:1], s[62:63]
	v_ashrrev_i32_e32 v229, 31, v228
	v_readlane_b32 s39, v254, 31
	v_readlane_b32 s30, v254, 26
	s_add_u32 s26, s0, 0x723e000
	v_readlane_b32 s38, v254, 30
	s_mov_b32 s39, s30
	v_lshlrev_b32_e32 v132, 3, v249
	s_addc_u32 s27, s1, 0
	v_lshlrev_b64 v[2:3], 11, v[228:229]
	v_lshl_add_u64 v[130:131], s[26:27], 0, v[2:3]
	v_readlane_b32 s29, v254, 25
	v_readlane_b32 s31, v254, 27
	v_lshlrev_b32_e32 v131, 11, v228
	v_add_u32_e32 v131, v131, v212
	buffer_load_dwordx2 v[138:139], v132, s[36:39], 0 offen
	s_mov_b32 s0, 0x20000
	buffer_load_dwordx2 v[140:141], v132, s[36:39], s0 offen
	s_mov_b32 s0, 0x1000
	buffer_load_dwordx2 v[142:143], v132, s[36:39], s0 offen
	s_mov_b32 s0, 0x21000
	buffer_load_dwordx2 v[144:145], v132, s[36:39], s0 offen
	s_mov_b32 s0, 0x8000
	buffer_load_dwordx2 v[146:147], v132, s[36:39], s0 offen
	s_mov_b32 s0, 0x28000
	buffer_load_dwordx2 v[148:149], v132, s[36:39], s0 offen
	s_mov_b32 s0, 0x9000
	buffer_load_dwordx2 v[150:151], v132, s[36:39], s0 offen
	s_mov_b32 s0, 0x29000
	buffer_load_dwordx2 v[152:153], v132, s[36:39], s0 offen
	s_mov_b32 s0, 0x2000
	buffer_load_dwordx2 v[154:155], v132, s[36:39], s0 offen
	s_mov_b32 s0, 0x22000
	buffer_load_dwordx2 v[156:157], v132, s[36:39], s0 offen
	s_mov_b32 s0, 0x3000
	buffer_load_dwordx2 v[158:159], v132, s[36:39], s0 offen
	s_mov_b32 s0, 0x23000
	buffer_load_dwordx2 v[160:161], v132, s[36:39], s0 offen
	s_mov_b32 s0, 0xa000
	buffer_load_dwordx2 v[162:163], v132, s[36:39], s0 offen
	s_mov_b32 s0, 0x2a000
	buffer_load_dwordx2 v[164:165], v132, s[36:39], s0 offen
	s_mov_b32 s0, 0xb000
	buffer_load_dwordx2 v[166:167], v132, s[36:39], s0 offen
	s_mov_b32 s0, 0x2b000
	buffer_load_dwordx2 v[168:169], v132, s[36:39], s0 offen
	s_mov_b32 s0, 0x4000
	buffer_load_dwordx2 v[170:171], v132, s[36:39], s0 offen
	s_mov_b32 s0, 0x24000
	buffer_load_dwordx2 v[172:173], v132, s[36:39], s0 offen
	s_mov_b32 s0, 0x5000
	buffer_load_dwordx2 v[174:175], v132, s[36:39], s0 offen
	s_mov_b32 s0, 0x25000
	buffer_load_dwordx2 v[176:177], v132, s[36:39], s0 offen
	s_mov_b32 s0, 0xc000
	buffer_load_dwordx2 v[178:179], v132, s[36:39], s0 offen
	s_mov_b32 s0, 0x2c000
	buffer_load_dwordx2 v[180:181], v132, s[36:39], s0 offen
	s_mov_b32 s0, 0xd000
	buffer_load_dwordx2 v[182:183], v132, s[36:39], s0 offen
	s_mov_b32 s0, 0x2d000
	buffer_load_dwordx2 v[184:185], v132, s[36:39], s0 offen
	s_mov_b32 s0, 0x6000
	buffer_load_dwordx2 v[186:187], v132, s[36:39], s0 offen
	s_mov_b32 s0, 0x26000
	buffer_load_dwordx2 v[188:189], v132, s[36:39], s0 offen
	s_mov_b32 s0, 0x7000
	buffer_load_dwordx2 v[190:191], v132, s[36:39], s0 offen
	s_mov_b32 s0, 0x27000
	buffer_load_dwordx2 v[192:193], v132, s[36:39], s0 offen
	s_waitcnt vmcnt(24)
	v_lshlrev_b32_e32 v2, 16, v138
	v_and_b32_e32 v3, 0xffff0000, v138
	v_lshlrev_b32_e32 v4, 16, v139
	v_and_b32_e32 v5, 0xffff0000, v139
	v_pk_add_f32 v[126:127], v[126:127], v[2:3]
	v_pk_add_f32 v[128:129], v[128:129], v[4:5]
	v_lshlrev_b32_e32 v2, 16, v140
	v_and_b32_e32 v3, 0xffff0000, v140
	v_lshlrev_b32_e32 v4, 16, v141
	v_and_b32_e32 v5, 0xffff0000, v141
	v_pk_add_f32 v[126:127], v[126:127], v[2:3]
	v_pk_add_f32 v[128:129], v[128:129], v[4:5]
	v_lshlrev_b32_e32 v2, 16, v142
	v_and_b32_e32 v3, 0xffff0000, v142
	v_lshlrev_b32_e32 v4, 16, v143
	v_and_b32_e32 v5, 0xffff0000, v143
	v_pk_add_f32 v[122:123], v[122:123], v[2:3]
	v_pk_add_f32 v[124:125], v[124:125], v[4:5]
	v_lshlrev_b32_e32 v2, 16, v144
	v_and_b32_e32 v3, 0xffff0000, v144
	v_lshlrev_b32_e32 v4, 16, v145
	v_and_b32_e32 v5, 0xffff0000, v145
	v_pk_add_f32 v[122:123], v[122:123], v[2:3]
	v_pk_add_f32 v[124:125], v[124:125], v[4:5]
	v_cvt_pk_bf16_f32 v2, v126, v127
	v_cvt_pk_bf16_f32 v3, v128, v129
	v_cvt_pk_bf16_f32 v4, v122, v123
	v_cvt_pk_bf16_f32 v5, v124, v125
	global_store_dwordx4 v131, v[2:5], s[26:27]
	s_nop 1
	s_mov_b32 s0, 0xe000
	buffer_load_dwordx2 v[138:139], v132, s[36:39], s0 offen
	s_mov_b32 s0, 0x2e000
	buffer_load_dwordx2 v[140:141], v132, s[36:39], s0 offen
	s_mov_b32 s0, 0xf000
	buffer_load_dwordx2 v[142:143], v132, s[36:39], s0 offen
	s_mov_b32 s0, 0x2f000
	buffer_load_dwordx2 v[144:145], v132, s[36:39], s0 offen
	s_waitcnt vmcnt(25)
	v_lshlrev_b32_e32 v2, 16, v146
	v_and_b32_e32 v3, 0xffff0000, v146
	v_lshlrev_b32_e32 v4, 16, v147
	v_and_b32_e32 v5, 0xffff0000, v147
	v_pk_add_f32 v[118:119], v[118:119], v[2:3]
	v_pk_add_f32 v[120:121], v[120:121], v[4:5]
	v_lshlrev_b32_e32 v2, 16, v148
	v_and_b32_e32 v3, 0xffff0000, v148
	v_lshlrev_b32_e32 v4, 16, v149
	v_and_b32_e32 v5, 0xffff0000, v149
	v_pk_add_f32 v[118:119], v[118:119], v[2:3]
	v_pk_add_f32 v[120:121], v[120:121], v[4:5]
	v_lshlrev_b32_e32 v2, 16, v150
	v_and_b32_e32 v3, 0xffff0000, v150
	v_lshlrev_b32_e32 v4, 16, v151
	v_and_b32_e32 v5, 0xffff0000, v151
	v_pk_add_f32 v[110:111], v[110:111], v[2:3]
	v_pk_add_f32 v[112:113], v[112:113], v[4:5]
	v_lshlrev_b32_e32 v2, 16, v152
	v_and_b32_e32 v3, 0xffff0000, v152
	v_lshlrev_b32_e32 v4, 16, v153
	v_and_b32_e32 v5, 0xffff0000, v153
	v_pk_add_f32 v[110:111], v[110:111], v[2:3]
	v_pk_add_f32 v[112:113], v[112:113], v[4:5]
	v_cvt_pk_bf16_f32 v2, v118, v119
	v_cvt_pk_bf16_f32 v3, v120, v121
	v_cvt_pk_bf16_f32 v4, v110, v111
	v_cvt_pk_bf16_f32 v5, v112, v113
	global_store_dwordx4 v131, v[2:5], s[26:27] offset:256
	s_nop 1
	s_mov_b32 s0, 0x10000
	buffer_load_dwordx2 v[146:147], v132, s[36:39], s0 offen
	s_mov_b32 s0, 0x30000
	buffer_load_dwordx2 v[148:149], v132, s[36:39], s0 offen
	s_mov_b32 s0, 0x11000
	buffer_load_dwordx2 v[150:151], v132, s[36:39], s0 offen
	s_mov_b32 s0, 0x31000
	buffer_load_dwordx2 v[152:153], v132, s[36:39], s0 offen
	s_waitcnt vmcnt(26)
	v_lshlrev_b32_e32 v2, 16, v154
	v_and_b32_e32 v3, 0xffff0000, v154
	v_lshlrev_b32_e32 v4, 16, v155
	v_and_b32_e32 v5, 0xffff0000, v155
	v_pk_add_f32 v[114:115], v[114:115], v[2:3]
	v_pk_add_f32 v[116:117], v[116:117], v[4:5]
	v_lshlrev_b32_e32 v2, 16, v156
	v_and_b32_e32 v3, 0xffff0000, v156
	v_lshlrev_b32_e32 v4, 16, v157
	v_and_b32_e32 v5, 0xffff0000, v157
	v_pk_add_f32 v[114:115], v[114:115], v[2:3]
	v_pk_add_f32 v[116:117], v[116:117], v[4:5]
	v_lshlrev_b32_e32 v2, 16, v158
	v_and_b32_e32 v3, 0xffff0000, v158
	v_lshlrev_b32_e32 v4, 16, v159
	v_and_b32_e32 v5, 0xffff0000, v159
	v_pk_add_f32 v[106:107], v[106:107], v[2:3]
	v_pk_add_f32 v[108:109], v[108:109], v[4:5]
	v_lshlrev_b32_e32 v2, 16, v160
	v_and_b32_e32 v3, 0xffff0000, v160
	v_lshlrev_b32_e32 v4, 16, v161
	v_and_b32_e32 v5, 0xffff0000, v161
	v_pk_add_f32 v[106:107], v[106:107], v[2:3]
	v_pk_add_f32 v[108:109], v[108:109], v[4:5]
	v_cvt_pk_bf16_f32 v2, v114, v115
	v_cvt_pk_bf16_f32 v3, v116, v117
	v_cvt_pk_bf16_f32 v4, v106, v107
	v_cvt_pk_bf16_f32 v5, v108, v109
	v_add_u32_e32 v130, 0x8000, v131
	global_store_dwordx4 v130, v[2:5], s[26:27]
	s_nop 1
	s_mov_b32 s0, 0x18000
	buffer_load_dwordx2 v[154:155], v132, s[36:39], s0 offen
	s_mov_b32 s0, 0x38000
	buffer_load_dwordx2 v[156:157], v132, s[36:39], s0 offen
	s_mov_b32 s0, 0x19000
	buffer_load_dwordx2 v[158:159], v132, s[36:39], s0 offen
	s_mov_b32 s0, 0x39000
	buffer_load_dwordx2 v[160:161], v132, s[36:39], s0 offen
	s_waitcnt vmcnt(27)
	v_lshlrev_b32_e32 v2, 16, v162
	v_and_b32_e32 v3, 0xffff0000, v162
	v_lshlrev_b32_e32 v4, 16, v163
	v_and_b32_e32 v5, 0xffff0000, v163
	v_pk_add_f32 v[102:103], v[102:103], v[2:3]
	v_pk_add_f32 v[104:105], v[104:105], v[4:5]
	v_lshlrev_b32_e32 v2, 16, v164
	v_and_b32_e32 v3, 0xffff0000, v164
	v_lshlrev_b32_e32 v4, 16, v165
	v_and_b32_e32 v5, 0xffff0000, v165
	v_pk_add_f32 v[102:103], v[102:103], v[2:3]
	v_pk_add_f32 v[104:105], v[104:105], v[4:5]
	v_lshlrev_b32_e32 v2, 16, v166
	v_and_b32_e32 v3, 0xffff0000, v166
	v_lshlrev_b32_e32 v4, 16, v167
	v_and_b32_e32 v5, 0xffff0000, v167
	v_pk_add_f32 v[94:95], v[94:95], v[2:3]
	v_pk_add_f32 v[96:97], v[96:97], v[4:5]
	v_lshlrev_b32_e32 v2, 16, v168
	v_and_b32_e32 v3, 0xffff0000, v168
	v_lshlrev_b32_e32 v4, 16, v169
	v_and_b32_e32 v5, 0xffff0000, v169
	v_pk_add_f32 v[94:95], v[94:95], v[2:3]
	v_pk_add_f32 v[96:97], v[96:97], v[4:5]
	v_cvt_pk_bf16_f32 v2, v102, v103
	v_cvt_pk_bf16_f32 v3, v104, v105
	v_cvt_pk_bf16_f32 v4, v94, v95
	v_cvt_pk_bf16_f32 v5, v96, v97
	v_add_u32_e32 v130, 0x8000, v131
	global_store_dwordx4 v130, v[2:5], s[26:27] offset:256
	s_nop 1
	s_mov_b32 s0, 0x12000
	buffer_load_dwordx2 v[162:163], v132, s[36:39], s0 offen
	s_mov_b32 s0, 0x32000
	buffer_load_dwordx2 v[164:165], v132, s[36:39], s0 offen
	s_mov_b32 s0, 0x13000
	buffer_load_dwordx2 v[166:167], v132, s[36:39], s0 offen
	s_mov_b32 s0, 0x33000
	buffer_load_dwordx2 v[168:169], v132, s[36:39], s0 offen
	s_waitcnt vmcnt(28)
	v_lshlrev_b32_e32 v2, 16, v170
	v_and_b32_e32 v3, 0xffff0000, v170
	v_lshlrev_b32_e32 v4, 16, v171
	v_and_b32_e32 v5, 0xffff0000, v171
	v_pk_add_f32 v[98:99], v[98:99], v[2:3]
	v_pk_add_f32 v[100:101], v[100:101], v[4:5]
	v_lshlrev_b32_e32 v2, 16, v172
	v_and_b32_e32 v3, 0xffff0000, v172
	v_lshlrev_b32_e32 v4, 16, v173
	v_and_b32_e32 v5, 0xffff0000, v173
	v_pk_add_f32 v[98:99], v[98:99], v[2:3]
	v_pk_add_f32 v[100:101], v[100:101], v[4:5]
	v_lshlrev_b32_e32 v2, 16, v174
	v_and_b32_e32 v3, 0xffff0000, v174
	v_lshlrev_b32_e32 v4, 16, v175
	v_and_b32_e32 v5, 0xffff0000, v175
	v_pk_add_f32 v[90:91], v[90:91], v[2:3]
	v_pk_add_f32 v[92:93], v[92:93], v[4:5]
	v_lshlrev_b32_e32 v2, 16, v176
	v_and_b32_e32 v3, 0xffff0000, v176
	v_lshlrev_b32_e32 v4, 16, v177
	v_and_b32_e32 v5, 0xffff0000, v177
	v_pk_add_f32 v[90:91], v[90:91], v[2:3]
	v_pk_add_f32 v[92:93], v[92:93], v[4:5]
	v_cvt_pk_bf16_f32 v2, v98, v99
	v_cvt_pk_bf16_f32 v3, v100, v101
	v_cvt_pk_bf16_f32 v4, v90, v91
	v_cvt_pk_bf16_f32 v5, v92, v93
	v_add_u32_e32 v130, 0x10000, v131
	global_store_dwordx4 v130, v[2:5], s[26:27]
	s_nop 1
	s_mov_b32 s0, 0x1a000
	buffer_load_dwordx2 v[170:171], v132, s[36:39], s0 offen
	s_mov_b32 s0, 0x3a000
	buffer_load_dwordx2 v[172:173], v132, s[36:39], s0 offen
	s_mov_b32 s0, 0x1b000
	buffer_load_dwordx2 v[174:175], v132, s[36:39], s0 offen
	s_mov_b32 s0, 0x3b000
	buffer_load_dwordx2 v[176:177], v132, s[36:39], s0 offen
	s_waitcnt vmcnt(29)
	v_lshlrev_b32_e32 v2, 16, v178
	v_and_b32_e32 v3, 0xffff0000, v178
	v_lshlrev_b32_e32 v4, 16, v179
	v_and_b32_e32 v5, 0xffff0000, v179
	v_pk_add_f32 v[86:87], v[86:87], v[2:3]
	v_pk_add_f32 v[88:89], v[88:89], v[4:5]
	v_lshlrev_b32_e32 v2, 16, v180
	v_and_b32_e32 v3, 0xffff0000, v180
	v_lshlrev_b32_e32 v4, 16, v181
	v_and_b32_e32 v5, 0xffff0000, v181
	v_pk_add_f32 v[86:87], v[86:87], v[2:3]
	v_pk_add_f32 v[88:89], v[88:89], v[4:5]
	v_lshlrev_b32_e32 v2, 16, v182
	v_and_b32_e32 v3, 0xffff0000, v182
	v_lshlrev_b32_e32 v4, 16, v183
	v_and_b32_e32 v5, 0xffff0000, v183
	v_pk_add_f32 v[78:79], v[78:79], v[2:3]
	v_pk_add_f32 v[80:81], v[80:81], v[4:5]
	v_lshlrev_b32_e32 v2, 16, v184
	v_and_b32_e32 v3, 0xffff0000, v184
	v_lshlrev_b32_e32 v4, 16, v185
	v_and_b32_e32 v5, 0xffff0000, v185
	v_pk_add_f32 v[78:79], v[78:79], v[2:3]
	v_pk_add_f32 v[80:81], v[80:81], v[4:5]
	v_cvt_pk_bf16_f32 v2, v86, v87
	v_cvt_pk_bf16_f32 v3, v88, v89
	v_cvt_pk_bf16_f32 v4, v78, v79
	v_cvt_pk_bf16_f32 v5, v80, v81
	v_add_u32_e32 v130, 0x10000, v131
	global_store_dwordx4 v130, v[2:5], s[26:27] offset:256
	s_nop 1
	s_mov_b32 s0, 0x14000
	buffer_load_dwordx2 v[178:179], v132, s[36:39], s0 offen
	s_mov_b32 s0, 0x34000
	buffer_load_dwordx2 v[180:181], v132, s[36:39], s0 offen
	s_mov_b32 s0, 0x15000
	buffer_load_dwordx2 v[182:183], v132, s[36:39], s0 offen
	s_mov_b32 s0, 0x35000
	buffer_load_dwordx2 v[184:185], v132, s[36:39], s0 offen
	s_waitcnt vmcnt(30)
	v_lshlrev_b32_e32 v2, 16, v186
	v_and_b32_e32 v3, 0xffff0000, v186
	v_lshlrev_b32_e32 v4, 16, v187
	v_and_b32_e32 v5, 0xffff0000, v187
	v_pk_add_f32 v[82:83], v[82:83], v[2:3]
	v_pk_add_f32 v[84:85], v[84:85], v[4:5]
	v_lshlrev_b32_e32 v2, 16, v188
	v_and_b32_e32 v3, 0xffff0000, v188
	v_lshlrev_b32_e32 v4, 16, v189
	v_and_b32_e32 v5, 0xffff0000, v189
	v_pk_add_f32 v[82:83], v[82:83], v[2:3]
	v_pk_add_f32 v[84:85], v[84:85], v[4:5]
	v_lshlrev_b32_e32 v2, 16, v190
	v_and_b32_e32 v3, 0xffff0000, v190
	v_lshlrev_b32_e32 v4, 16, v191
	v_and_b32_e32 v5, 0xffff0000, v191
	v_pk_add_f32 v[74:75], v[74:75], v[2:3]
	v_pk_add_f32 v[76:77], v[76:77], v[4:5]
	v_lshlrev_b32_e32 v2, 16, v192
	v_and_b32_e32 v3, 0xffff0000, v192
	v_lshlrev_b32_e32 v4, 16, v193
	v_and_b32_e32 v5, 0xffff0000, v193
	v_pk_add_f32 v[74:75], v[74:75], v[2:3]
	v_pk_add_f32 v[76:77], v[76:77], v[4:5]
	v_cvt_pk_bf16_f32 v2, v82, v83
	v_cvt_pk_bf16_f32 v3, v84, v85
	v_cvt_pk_bf16_f32 v4, v74, v75
	v_cvt_pk_bf16_f32 v5, v76, v77
	v_add_u32_e32 v130, 0x18000, v131
	global_store_dwordx4 v130, v[2:5], s[26:27]
	s_nop 1
	s_mov_b32 s0, 0x1c000
	buffer_load_dwordx2 v[186:187], v132, s[36:39], s0 offen
	s_mov_b32 s0, 0x3c000
	buffer_load_dwordx2 v[188:189], v132, s[36:39], s0 offen
	s_mov_b32 s0, 0x1d000
	buffer_load_dwordx2 v[190:191], v132, s[36:39], s0 offen
	s_mov_b32 s0, 0x3d000
	buffer_load_dwordx2 v[192:193], v132, s[36:39], s0 offen
	s_waitcnt vmcnt(30)
	v_lshlrev_b32_e32 v2, 16, v138
	v_and_b32_e32 v3, 0xffff0000, v138
	v_lshlrev_b32_e32 v4, 16, v139
	v_and_b32_e32 v5, 0xffff0000, v139
	v_pk_add_f32 v[70:71], v[70:71], v[2:3]
	v_pk_add_f32 v[72:73], v[72:73], v[4:5]
	v_lshlrev_b32_e32 v2, 16, v140
	v_and_b32_e32 v3, 0xffff0000, v140
	v_lshlrev_b32_e32 v4, 16, v141
	v_and_b32_e32 v5, 0xffff0000, v141
	v_pk_add_f32 v[70:71], v[70:71], v[2:3]
	v_pk_add_f32 v[72:73], v[72:73], v[4:5]
	v_lshlrev_b32_e32 v2, 16, v142
	v_and_b32_e32 v3, 0xffff0000, v142
	v_lshlrev_b32_e32 v4, 16, v143
	v_and_b32_e32 v5, 0xffff0000, v143
	v_pk_add_f32 v[66:67], v[66:67], v[2:3]
	v_pk_add_f32 v[68:69], v[68:69], v[4:5]
	v_lshlrev_b32_e32 v2, 16, v144
	v_and_b32_e32 v3, 0xffff0000, v144
	v_lshlrev_b32_e32 v4, 16, v145
	v_and_b32_e32 v5, 0xffff0000, v145
	v_pk_add_f32 v[66:67], v[66:67], v[2:3]
	v_pk_add_f32 v[68:69], v[68:69], v[4:5]
	v_cvt_pk_bf16_f32 v2, v70, v71
	v_cvt_pk_bf16_f32 v3, v72, v73
	v_cvt_pk_bf16_f32 v4, v66, v67
	v_cvt_pk_bf16_f32 v5, v68, v69
	v_add_u32_e32 v130, 0x18000, v131
	global_store_dwordx4 v130, v[2:5], s[26:27] offset:256
	s_nop 1
	s_mov_b32 s0, 0x16000
	buffer_load_dwordx2 v[138:139], v132, s[36:39], s0 offen
	s_mov_b32 s0, 0x36000
	buffer_load_dwordx2 v[140:141], v132, s[36:39], s0 offen
	s_mov_b32 s0, 0x17000
	buffer_load_dwordx2 v[142:143], v132, s[36:39], s0 offen
	s_mov_b32 s0, 0x37000
	buffer_load_dwordx2 v[144:145], v132, s[36:39], s0 offen
	s_waitcnt vmcnt(30)
	v_lshlrev_b32_e32 v2, 16, v146
	v_and_b32_e32 v3, 0xffff0000, v146
	v_lshlrev_b32_e32 v4, 16, v147
	v_and_b32_e32 v5, 0xffff0000, v147
	v_pk_add_f32 v[62:63], v[62:63], v[2:3]
	v_pk_add_f32 v[64:65], v[64:65], v[4:5]
	v_lshlrev_b32_e32 v2, 16, v148
	v_and_b32_e32 v3, 0xffff0000, v148
	v_lshlrev_b32_e32 v4, 16, v149
	v_and_b32_e32 v5, 0xffff0000, v149
	v_pk_add_f32 v[62:63], v[62:63], v[2:3]
	v_pk_add_f32 v[64:65], v[64:65], v[4:5]
	v_lshlrev_b32_e32 v2, 16, v150
	v_and_b32_e32 v3, 0xffff0000, v150
	v_lshlrev_b32_e32 v4, 16, v151
	v_and_b32_e32 v5, 0xffff0000, v151
	v_pk_add_f32 v[58:59], v[58:59], v[2:3]
	v_pk_add_f32 v[60:61], v[60:61], v[4:5]
	v_lshlrev_b32_e32 v2, 16, v152
	v_and_b32_e32 v3, 0xffff0000, v152
	v_lshlrev_b32_e32 v4, 16, v153
	v_and_b32_e32 v5, 0xffff0000, v153
	v_pk_add_f32 v[58:59], v[58:59], v[2:3]
	v_pk_add_f32 v[60:61], v[60:61], v[4:5]
	v_cvt_pk_bf16_f32 v2, v62, v63
	v_cvt_pk_bf16_f32 v3, v64, v65
	v_cvt_pk_bf16_f32 v4, v58, v59
	v_cvt_pk_bf16_f32 v5, v60, v61
	v_add_u32_e32 v130, 0x40000, v131
	global_store_dwordx4 v130, v[2:5], s[26:27]
	s_nop 1
	s_mov_b32 s0, 0x1e000
	buffer_load_dwordx2 v[146:147], v132, s[36:39], s0 offen
	s_mov_b32 s0, 0x3e000
	buffer_load_dwordx2 v[148:149], v132, s[36:39], s0 offen
	s_mov_b32 s0, 0x1f000
	buffer_load_dwordx2 v[150:151], v132, s[36:39], s0 offen
	s_mov_b32 s0, 0x3f000
	buffer_load_dwordx2 v[152:153], v132, s[36:39], s0 offen
	s_waitcnt vmcnt(30)
	v_lshlrev_b32_e32 v2, 16, v154
	v_and_b32_e32 v3, 0xffff0000, v154
	v_lshlrev_b32_e32 v4, 16, v155
	v_and_b32_e32 v5, 0xffff0000, v155
	v_pk_add_f32 v[54:55], v[54:55], v[2:3]
	v_pk_add_f32 v[56:57], v[56:57], v[4:5]
	v_lshlrev_b32_e32 v2, 16, v156
	v_and_b32_e32 v3, 0xffff0000, v156
	v_lshlrev_b32_e32 v4, 16, v157
	v_and_b32_e32 v5, 0xffff0000, v157
	v_pk_add_f32 v[54:55], v[54:55], v[2:3]
	v_pk_add_f32 v[56:57], v[56:57], v[4:5]
	v_lshlrev_b32_e32 v2, 16, v158
	v_and_b32_e32 v3, 0xffff0000, v158
	v_lshlrev_b32_e32 v4, 16, v159
	v_and_b32_e32 v5, 0xffff0000, v159
	v_pk_add_f32 v[46:47], v[46:47], v[2:3]
	v_pk_add_f32 v[48:49], v[48:49], v[4:5]
	v_lshlrev_b32_e32 v2, 16, v160
	v_and_b32_e32 v3, 0xffff0000, v160
	v_lshlrev_b32_e32 v4, 16, v161
	v_and_b32_e32 v5, 0xffff0000, v161
	v_pk_add_f32 v[46:47], v[46:47], v[2:3]
	v_pk_add_f32 v[48:49], v[48:49], v[4:5]
	v_cvt_pk_bf16_f32 v2, v54, v55
	v_cvt_pk_bf16_f32 v3, v56, v57
	v_cvt_pk_bf16_f32 v4, v46, v47
	v_cvt_pk_bf16_f32 v5, v48, v49
	v_add_u32_e32 v130, 0x40000, v131
	global_store_dwordx4 v130, v[2:5], s[26:27] offset:256
	s_nop 1
	s_waitcnt vmcnt(26)
	v_lshlrev_b32_e32 v2, 16, v162
	v_and_b32_e32 v3, 0xffff0000, v162
	v_lshlrev_b32_e32 v4, 16, v163
	v_and_b32_e32 v5, 0xffff0000, v163
	v_pk_add_f32 v[50:51], v[50:51], v[2:3]
	v_pk_add_f32 v[52:53], v[52:53], v[4:5]
	v_lshlrev_b32_e32 v2, 16, v164
	v_and_b32_e32 v3, 0xffff0000, v164
	v_lshlrev_b32_e32 v4, 16, v165
	v_and_b32_e32 v5, 0xffff0000, v165
	v_pk_add_f32 v[50:51], v[50:51], v[2:3]
	v_pk_add_f32 v[52:53], v[52:53], v[4:5]
	v_lshlrev_b32_e32 v2, 16, v166
	v_and_b32_e32 v3, 0xffff0000, v166
	v_lshlrev_b32_e32 v4, 16, v167
	v_and_b32_e32 v5, 0xffff0000, v167
	v_pk_add_f32 v[42:43], v[42:43], v[2:3]
	v_pk_add_f32 v[44:45], v[44:45], v[4:5]
	v_lshlrev_b32_e32 v2, 16, v168
	v_and_b32_e32 v3, 0xffff0000, v168
	v_lshlrev_b32_e32 v4, 16, v169
	v_and_b32_e32 v5, 0xffff0000, v169
	v_pk_add_f32 v[42:43], v[42:43], v[2:3]
	v_pk_add_f32 v[44:45], v[44:45], v[4:5]
	v_cvt_pk_bf16_f32 v2, v50, v51
	v_cvt_pk_bf16_f32 v3, v52, v53
	v_cvt_pk_bf16_f32 v4, v42, v43
	v_cvt_pk_bf16_f32 v5, v44, v45
	v_add_u32_e32 v130, 0x48000, v131
	global_store_dwordx4 v130, v[2:5], s[26:27]
	s_nop 1
	s_waitcnt vmcnt(22)
	v_lshlrev_b32_e32 v2, 16, v170
	v_and_b32_e32 v3, 0xffff0000, v170
	v_lshlrev_b32_e32 v4, 16, v171
	v_and_b32_e32 v5, 0xffff0000, v171
	v_pk_add_f32 v[38:39], v[38:39], v[2:3]
	v_pk_add_f32 v[40:41], v[40:41], v[4:5]
	v_lshlrev_b32_e32 v2, 16, v172
	v_and_b32_e32 v3, 0xffff0000, v172
	v_lshlrev_b32_e32 v4, 16, v173
	v_and_b32_e32 v5, 0xffff0000, v173
	v_pk_add_f32 v[38:39], v[38:39], v[2:3]
	v_pk_add_f32 v[40:41], v[40:41], v[4:5]
	v_lshlrev_b32_e32 v2, 16, v174
	v_and_b32_e32 v3, 0xffff0000, v174
	v_lshlrev_b32_e32 v4, 16, v175
	v_and_b32_e32 v5, 0xffff0000, v175
	v_pk_add_f32 v[30:31], v[30:31], v[2:3]
	v_pk_add_f32 v[32:33], v[32:33], v[4:5]
	v_lshlrev_b32_e32 v2, 16, v176
	v_and_b32_e32 v3, 0xffff0000, v176
	v_lshlrev_b32_e32 v4, 16, v177
	v_and_b32_e32 v5, 0xffff0000, v177
	v_pk_add_f32 v[30:31], v[30:31], v[2:3]
	v_pk_add_f32 v[32:33], v[32:33], v[4:5]
	v_cvt_pk_bf16_f32 v2, v38, v39
	v_cvt_pk_bf16_f32 v3, v40, v41
	v_cvt_pk_bf16_f32 v4, v30, v31
	v_cvt_pk_bf16_f32 v5, v32, v33
	v_add_u32_e32 v130, 0x48000, v131
	global_store_dwordx4 v130, v[2:5], s[26:27] offset:256
	s_nop 1
	s_waitcnt vmcnt(18)
	v_lshlrev_b32_e32 v2, 16, v178
	v_and_b32_e32 v3, 0xffff0000, v178
	v_lshlrev_b32_e32 v4, 16, v179
	v_and_b32_e32 v5, 0xffff0000, v179
	v_pk_add_f32 v[34:35], v[34:35], v[2:3]
	v_pk_add_f32 v[36:37], v[36:37], v[4:5]
	v_lshlrev_b32_e32 v2, 16, v180
	v_and_b32_e32 v3, 0xffff0000, v180
	v_lshlrev_b32_e32 v4, 16, v181
	v_and_b32_e32 v5, 0xffff0000, v181
	v_pk_add_f32 v[34:35], v[34:35], v[2:3]
	v_pk_add_f32 v[36:37], v[36:37], v[4:5]
	v_lshlrev_b32_e32 v2, 16, v182
	v_and_b32_e32 v3, 0xffff0000, v182
	v_lshlrev_b32_e32 v4, 16, v183
	v_and_b32_e32 v5, 0xffff0000, v183
	v_pk_add_f32 v[26:27], v[26:27], v[2:3]
	v_pk_add_f32 v[28:29], v[28:29], v[4:5]
	v_lshlrev_b32_e32 v2, 16, v184
	v_and_b32_e32 v3, 0xffff0000, v184
	v_lshlrev_b32_e32 v4, 16, v185
	v_and_b32_e32 v5, 0xffff0000, v185
	v_pk_add_f32 v[26:27], v[26:27], v[2:3]
	v_pk_add_f32 v[28:29], v[28:29], v[4:5]
	v_cvt_pk_bf16_f32 v2, v34, v35
	v_cvt_pk_bf16_f32 v3, v36, v37
	v_cvt_pk_bf16_f32 v4, v26, v27
	v_cvt_pk_bf16_f32 v5, v28, v29
	v_add_u32_e32 v130, 0x50000, v131
	global_store_dwordx4 v130, v[2:5], s[26:27]
	s_nop 1
	s_waitcnt vmcnt(14)
	v_lshlrev_b32_e32 v2, 16, v186
	v_and_b32_e32 v3, 0xffff0000, v186
	v_lshlrev_b32_e32 v4, 16, v187
	v_and_b32_e32 v5, 0xffff0000, v187
	v_pk_add_f32 v[22:23], v[22:23], v[2:3]
	v_pk_add_f32 v[24:25], v[24:25], v[4:5]
	v_lshlrev_b32_e32 v2, 16, v188
	v_and_b32_e32 v3, 0xffff0000, v188
	v_lshlrev_b32_e32 v4, 16, v189
	v_and_b32_e32 v5, 0xffff0000, v189
	v_pk_add_f32 v[22:23], v[22:23], v[2:3]
	v_pk_add_f32 v[24:25], v[24:25], v[4:5]
	v_lshlrev_b32_e32 v2, 16, v190
	v_and_b32_e32 v3, 0xffff0000, v190
	v_lshlrev_b32_e32 v4, 16, v191
	v_and_b32_e32 v5, 0xffff0000, v191
	v_pk_add_f32 v[14:15], v[14:15], v[2:3]
	v_pk_add_f32 v[16:17], v[16:17], v[4:5]
	v_lshlrev_b32_e32 v2, 16, v192
	v_and_b32_e32 v3, 0xffff0000, v192
	v_lshlrev_b32_e32 v4, 16, v193
	v_and_b32_e32 v5, 0xffff0000, v193
	v_pk_add_f32 v[14:15], v[14:15], v[2:3]
	v_pk_add_f32 v[16:17], v[16:17], v[4:5]
	v_cvt_pk_bf16_f32 v2, v22, v23
	v_cvt_pk_bf16_f32 v3, v24, v25
	v_cvt_pk_bf16_f32 v4, v14, v15
	v_cvt_pk_bf16_f32 v5, v16, v17
	v_add_u32_e32 v130, 0x50000, v131
	global_store_dwordx4 v130, v[2:5], s[26:27] offset:256
	s_nop 1
	s_waitcnt vmcnt(10)
	v_lshlrev_b32_e32 v2, 16, v138
	v_and_b32_e32 v3, 0xffff0000, v138
	v_lshlrev_b32_e32 v4, 16, v139
	v_and_b32_e32 v5, 0xffff0000, v139
	v_pk_add_f32 v[18:19], v[18:19], v[2:3]
	v_pk_add_f32 v[20:21], v[20:21], v[4:5]
	v_lshlrev_b32_e32 v2, 16, v140
	v_and_b32_e32 v3, 0xffff0000, v140
	v_lshlrev_b32_e32 v4, 16, v141
	v_and_b32_e32 v5, 0xffff0000, v141
	v_pk_add_f32 v[18:19], v[18:19], v[2:3]
	v_pk_add_f32 v[20:21], v[20:21], v[4:5]
	v_lshlrev_b32_e32 v2, 16, v142
	v_and_b32_e32 v3, 0xffff0000, v142
	v_lshlrev_b32_e32 v4, 16, v143
	v_and_b32_e32 v5, 0xffff0000, v143
	v_pk_add_f32 v[136:137], v[136:137], v[2:3]
	v_pk_add_f32 v[134:135], v[134:135], v[4:5]
	v_lshlrev_b32_e32 v2, 16, v144
	v_and_b32_e32 v3, 0xffff0000, v144
	v_lshlrev_b32_e32 v4, 16, v145
	v_and_b32_e32 v5, 0xffff0000, v145
	v_pk_add_f32 v[136:137], v[136:137], v[2:3]
	v_pk_add_f32 v[134:135], v[134:135], v[4:5]
	v_cvt_pk_bf16_f32 v2, v18, v19
	v_cvt_pk_bf16_f32 v3, v20, v21
	v_cvt_pk_bf16_f32 v4, v136, v137
	v_cvt_pk_bf16_f32 v5, v134, v135
	v_add_u32_e32 v130, 0x58000, v131
	global_store_dwordx4 v130, v[2:5], s[26:27]
	s_nop 1
	s_waitcnt vmcnt(6)
	v_lshlrev_b32_e32 v2, 16, v146
	v_and_b32_e32 v3, 0xffff0000, v146
	v_lshlrev_b32_e32 v4, 16, v147
	v_and_b32_e32 v5, 0xffff0000, v147
	v_pk_add_f32 v[6:7], v[6:7], v[2:3]
	v_pk_add_f32 v[8:9], v[8:9], v[4:5]
	v_lshlrev_b32_e32 v2, 16, v148
	v_and_b32_e32 v3, 0xffff0000, v148
	v_lshlrev_b32_e32 v4, 16, v149
	v_and_b32_e32 v5, 0xffff0000, v149
	v_pk_add_f32 v[6:7], v[6:7], v[2:3]
	v_pk_add_f32 v[8:9], v[8:9], v[4:5]
	v_lshlrev_b32_e32 v2, 16, v150
	v_and_b32_e32 v3, 0xffff0000, v150
	v_lshlrev_b32_e32 v4, 16, v151
	v_and_b32_e32 v5, 0xffff0000, v151
	v_pk_add_f32 v[12:13], v[12:13], v[2:3]
	v_pk_add_f32 v[10:11], v[10:11], v[4:5]
	v_lshlrev_b32_e32 v2, 16, v152
	v_and_b32_e32 v3, 0xffff0000, v152
	v_lshlrev_b32_e32 v4, 16, v153
	v_and_b32_e32 v5, 0xffff0000, v153
	v_pk_add_f32 v[12:13], v[12:13], v[2:3]
	v_pk_add_f32 v[10:11], v[10:11], v[4:5]
	v_cvt_pk_bf16_f32 v2, v6, v7
	v_cvt_pk_bf16_f32 v3, v8, v9
	v_cvt_pk_bf16_f32 v4, v12, v13
	v_cvt_pk_bf16_f32 v5, v10, v11
	v_add_u32_e32 v130, 0x58000, v131
	global_store_dwordx4 v130, v[2:5], s[26:27] offset:256
	s_nop 1
	s_mov_b32 s26, s38
	v_writelane_b32 v254, s24, 28
	v_writelane_b32 v254, s25, 29
	v_writelane_b32 v254, s26, 30
	v_writelane_b32 v254, s27, 31

.LBB0_820:
	s_ashr_i32 s1, s91, 2
	s_and_b32 s21, s1, 0xffffffc0
	s_lshl_b32 s1, s31, 8
	s_add_i32 s21, s21, s1
	v_and_b32_e32 v0, 15, v230
	v_add_u32_e32 v142, s21, v0
	s_lshr_b32 s0, s91, 1
	s_and_b32 s0, s0, 0x60
	s_lshl_b32 s1, s37, 8
	s_or_b32 s0, s1, s0
	v_lshrrev_b32_e32 v0, 1, v230
	v_and_b32_e32 v0, -8, v0
	v_add_u32_e32 v143, s0, v0
	v_lshlrev_b32_e32 v144, 12, v142
	v_lshl_add_u32 v144, v143, 2, v144
	v_lshlrev_b32_e32 v145, 11, v142
	v_lshl_add_u32 v145, v143, 1, v145
	v_lshlrev_b32_e32 v146, 2, v143
	s_mov_b32 s30, 0
	s_mov_b32 s31, s71
	s_xor_b64 s[30:31], s[30:31], s[12:13]
	s_mov_b32 s28, 0
	s_mov_b32 s29, s71
	s_xor_b64 s[28:29], s[28:29], s[14:15]
	s_sub_u32 s28, s28, 0x1000000
	s_subb_u32 s29, s29, 0
	s_cmp_lt_u32 s21, 0x1000
	s_cselect_b32 s28, s30, s28
	s_cselect_b32 s29, s31, s29
	s_mov_b32 s0, 0
	s_mov_b32 s1, s71
	s_xor_b64 s[0:1], s[0:1], s[62:63]
	s_add_u32 s8, s0, s18
	s_addc_u32 s9, s1, s19
	s_add_u32 s34, s8, 0x4a02000
	s_addc_u32 s35, s9, 0
	s_add_u32 s38, s0, 0xc23e000
	s_addc_u32 s39, s1, 0
	s_add_i32 s1, s21, 0xfffff000
	s_lshr_b32 s1, s1, 10
	s_mulk_i32 s1, 0x1800
	s_add_i32 s52, s1, 0x1800
	s_cmp_lt_u32 s21, 0x1000
	s_cselect_b32 s52, 0, s52
	s_lshl_b32 s52, s52, 2
	s_add_u32 s34, s34, s52
	s_addc_u32 s35, s35, 0
	global_load_dwordx4 v[152:155], v146, s[34:35]
	global_load_dwordx4 v[156:159], v146, s[34:35] offset:16
	global_load_dwordx4 v[160:163], v146, s[34:35] offset:512
	global_load_dwordx4 v[164:167], v146, s[34:35] offset:528
	global_load_dwordx4 v[168:171], v144, s[28:29]
	global_load_dwordx4 v[172:175], v144, s[28:29] offset:16
	global_load_dwordx4 v[176:179], v144, s[28:29] offset:512
	global_load_dwordx4 v[180:183], v144, s[28:29] offset:528
	v_add_u32_e32 v147, 0x10000, v144
	global_load_dwordx4 v[184:187], v147, s[28:29]
	global_load_dwordx4 v[188:191], v147, s[28:29] offset:16
	global_load_dwordx4 v[192:195], v147, s[28:29] offset:512
	global_load_dwordx4 v[202:205], v147, s[28:29] offset:528
	v_add_u32_e32 v147, 0x20000, v144
	global_load_dwordx4 v[206:209], v147, s[28:29]
	global_load_dwordx4 v[210:213], v147, s[28:29] offset:16
	global_load_dwordx4 v[214:217], v147, s[28:29] offset:512
	global_load_dwordx4 v[218:221], v147, s[28:29] offset:528
	s_mov_b32 s0, 0x3fb504f3
	s_waitcnt vmcnt(8)
	v_pk_mul_f32 v[128:129], v[128:129], v[154:155]
	v_pk_mul_f32 v[126:127], v[126:127], v[152:153]
	v_pk_fma_f32 v[128:129], v[170:171], s[0:1], v[128:129] op_sel_hi:[1,0,1]
	v_pk_fma_f32 v[126:127], v[168:169], s[0:1], v[126:127] op_sel_hi:[1,0,1]
	v_pk_mul_f32 v[124:125], v[124:125], v[158:159]
	v_pk_mul_f32 v[122:123], v[122:123], v[156:157]
	v_pk_fma_f32 v[124:125], v[174:175], s[0:1], v[124:125] op_sel_hi:[1,0,1]
	v_pk_fma_f32 v[122:123], v[172:173], s[0:1], v[122:123] op_sel_hi:[1,0,1]
	v_pk_mul_f32 v[120:121], v[120:121], v[162:163]
	v_pk_mul_f32 v[118:119], v[118:119], v[160:161]
	v_pk_fma_f32 v[120:121], v[178:179], s[0:1], v[120:121] op_sel_hi:[1,0,1]
	v_pk_fma_f32 v[118:119], v[176:177], s[0:1], v[118:119] op_sel_hi:[1,0,1]
	v_pk_mul_f32 v[116:117], v[116:117], v[166:167]
	v_pk_mul_f32 v[114:115], v[114:115], v[164:165]
	v_pk_fma_f32 v[116:117], v[182:183], s[0:1], v[116:117] op_sel_hi:[1,0,1]
	v_pk_fma_f32 v[114:115], v[180:181], s[0:1], v[114:115] op_sel_hi:[1,0,1]
	v_cvt_pk_bf16_f32 v126, v126, v127
	v_cvt_pk_bf16_f32 v127, v128, v129
	v_cvt_pk_bf16_f32 v128, v122, v123
	v_cvt_pk_bf16_f32 v129, v124, v125
	global_store_dwordx4 v145, v[126:129], s[38:39]
	v_cvt_pk_bf16_f32 v118, v118, v119
	v_cvt_pk_bf16_f32 v119, v120, v121
	v_cvt_pk_bf16_f32 v120, v114, v115
	v_cvt_pk_bf16_f32 v121, v116, v117
	global_store_dwordx4 v145, v[118:121], s[38:39] offset:256
	v_add_u32_e32 v147, 0x30000, v144
	global_load_dwordx4 v[168:171], v147, s[28:29]
	global_load_dwordx4 v[172:175], v147, s[28:29] offset:16
	global_load_dwordx4 v[176:179], v147, s[28:29] offset:512
	global_load_dwordx4 v[180:183], v147, s[28:29] offset:528
	s_waitcnt vmcnt(10)
	v_pk_mul_f32 v[112:113], v[112:113], v[154:155]
	v_pk_mul_f32 v[110:111], v[110:111], v[152:153]
	v_pk_fma_f32 v[112:113], v[186:187], s[0:1], v[112:113] op_sel_hi:[1,0,1]
	v_pk_fma_f32 v[110:111], v[184:185], s[0:1], v[110:111] op_sel_hi:[1,0,1]
	v_pk_mul_f32 v[108:109], v[108:109], v[158:159]
	v_pk_mul_f32 v[106:107], v[106:107], v[156:157]
	v_pk_fma_f32 v[108:109], v[190:191], s[0:1], v[108:109] op_sel_hi:[1,0,1]
	v_pk_fma_f32 v[106:107], v[188:189], s[0:1], v[106:107] op_sel_hi:[1,0,1]
	v_pk_mul_f32 v[104:105], v[104:105], v[162:163]
	v_pk_mul_f32 v[102:103], v[102:103], v[160:161]
	v_pk_fma_f32 v[104:105], v[194:195], s[0:1], v[104:105] op_sel_hi:[1,0,1]
	v_pk_fma_f32 v[102:103], v[192:193], s[0:1], v[102:103] op_sel_hi:[1,0,1]
	v_pk_mul_f32 v[100:101], v[100:101], v[166:167]
	v_pk_mul_f32 v[98:99], v[98:99], v[164:165]
	v_pk_fma_f32 v[100:101], v[204:205], s[0:1], v[100:101] op_sel_hi:[1,0,1]
	v_pk_fma_f32 v[98:99], v[202:203], s[0:1], v[98:99] op_sel_hi:[1,0,1]
	v_add_u32_e32 v148, 0x8000, v145
	v_cvt_pk_bf16_f32 v110, v110, v111
	v_cvt_pk_bf16_f32 v111, v112, v113
	v_cvt_pk_bf16_f32 v112, v106, v107
	v_cvt_pk_bf16_f32 v113, v108, v109
	global_store_dwordx4 v148, v[110:113], s[38:39]
	v_cvt_pk_bf16_f32 v102, v102, v103
	v_cvt_pk_bf16_f32 v103, v104, v105
	v_cvt_pk_bf16_f32 v104, v98, v99
	v_cvt_pk_bf16_f32 v105, v100, v101
	global_store_dwordx4 v148, v[102:105], s[38:39] offset:256
	v_add_u32_e32 v147, 0x80000, v144
	global_load_dwordx4 v[184:187], v147, s[28:29]
	global_load_dwordx4 v[188:191], v147, s[28:29] offset:16
	global_load_dwordx4 v[192:195], v147, s[28:29] offset:512
	global_load_dwordx4 v[202:205], v147, s[28:29] offset:528
	s_waitcnt vmcnt(12)
	v_pk_mul_f32 v[96:97], v[96:97], v[154:155]
	v_pk_mul_f32 v[94:95], v[94:95], v[152:153]
	v_pk_fma_f32 v[96:97], v[208:209], s[0:1], v[96:97] op_sel_hi:[1,0,1]
	v_pk_fma_f32 v[94:95], v[206:207], s[0:1], v[94:95] op_sel_hi:[1,0,1]
	v_pk_mul_f32 v[92:93], v[92:93], v[158:159]
	v_pk_mul_f32 v[90:91], v[90:91], v[156:157]
	v_pk_fma_f32 v[92:93], v[212:213], s[0:1], v[92:93] op_sel_hi:[1,0,1]
	v_pk_fma_f32 v[90:91], v[210:211], s[0:1], v[90:91] op_sel_hi:[1,0,1]
	v_pk_mul_f32 v[88:89], v[88:89], v[162:163]
	v_pk_mul_f32 v[86:87], v[86:87], v[160:161]
	v_pk_fma_f32 v[88:89], v[216:217], s[0:1], v[88:89] op_sel_hi:[1,0,1]
	v_pk_fma_f32 v[86:87], v[214:215], s[0:1], v[86:87] op_sel_hi:[1,0,1]
	v_pk_mul_f32 v[84:85], v[84:85], v[166:167]
	v_pk_mul_f32 v[82:83], v[82:83], v[164:165]
	v_pk_fma_f32 v[84:85], v[220:221], s[0:1], v[84:85] op_sel_hi:[1,0,1]
	v_pk_fma_f32 v[82:83], v[218:219], s[0:1], v[82:83] op_sel_hi:[1,0,1]
	v_add_u32_e32 v148, 0x10000, v145
	v_cvt_pk_bf16_f32 v94, v94, v95
	v_cvt_pk_bf16_f32 v95, v96, v97
	v_cvt_pk_bf16_f32 v96, v90, v91
	v_cvt_pk_bf16_f32 v97, v92, v93
	global_store_dwordx4 v148, v[94:97], s[38:39]
	v_cvt_pk_bf16_f32 v86, v86, v87
	v_cvt_pk_bf16_f32 v87, v88, v89
	v_cvt_pk_bf16_f32 v88, v82, v83
	v_cvt_pk_bf16_f32 v89, v84, v85
	global_store_dwordx4 v148, v[86:89], s[38:39] offset:256
	v_add_u32_e32 v147, 0x90000, v144
	global_load_dwordx4 v[206:209], v147, s[28:29]
	global_load_dwordx4 v[210:213], v147, s[28:29] offset:16
	global_load_dwordx4 v[214:217], v147, s[28:29] offset:512
	global_load_dwordx4 v[218:221], v147, s[28:29] offset:528
	s_waitcnt vmcnt(12)
	v_pk_mul_f32 v[80:81], v[80:81], v[154:155]
	v_pk_mul_f32 v[78:79], v[78:79], v[152:153]
	v_pk_fma_f32 v[80:81], v[170:171], s[0:1], v[80:81] op_sel_hi:[1,0,1]
	v_pk_fma_f32 v[78:79], v[168:169], s[0:1], v[78:79] op_sel_hi:[1,0,1]
	v_pk_mul_f32 v[76:77], v[76:77], v[158:159]
	v_pk_mul_f32 v[74:75], v[74:75], v[156:157]
	v_pk_fma_f32 v[76:77], v[174:175], s[0:1], v[76:77] op_sel_hi:[1,0,1]
	v_pk_fma_f32 v[74:75], v[172:173], s[0:1], v[74:75] op_sel_hi:[1,0,1]
	v_pk_mul_f32 v[72:73], v[72:73], v[162:163]
	v_pk_mul_f32 v[70:71], v[70:71], v[160:161]
	v_pk_fma_f32 v[72:73], v[178:179], s[0:1], v[72:73] op_sel_hi:[1,0,1]
	v_pk_fma_f32 v[70:71], v[176:177], s[0:1], v[70:71] op_sel_hi:[1,0,1]
	v_pk_mul_f32 v[68:69], v[68:69], v[166:167]
	v_pk_mul_f32 v[66:67], v[66:67], v[164:165]
	v_pk_fma_f32 v[68:69], v[182:183], s[0:1], v[68:69] op_sel_hi:[1,0,1]
	v_pk_fma_f32 v[66:67], v[180:181], s[0:1], v[66:67] op_sel_hi:[1,0,1]
	v_add_u32_e32 v148, 0x18000, v145
	v_cvt_pk_bf16_f32 v78, v78, v79
	v_cvt_pk_bf16_f32 v79, v80, v81
	v_cvt_pk_bf16_f32 v80, v74, v75
	v_cvt_pk_bf16_f32 v81, v76, v77
	global_store_dwordx4 v148, v[78:81], s[38:39]
	v_cvt_pk_bf16_f32 v70, v70, v71
	v_cvt_pk_bf16_f32 v71, v72, v73
	v_cvt_pk_bf16_f32 v72, v66, v67
	v_cvt_pk_bf16_f32 v73, v68, v69
	global_store_dwordx4 v148, v[70:73], s[38:39] offset:256
	v_add_u32_e32 v147, 0xa0000, v144
	global_load_dwordx4 v[168:171], v147, s[28:29]
	global_load_dwordx4 v[172:175], v147, s[28:29] offset:16
	global_load_dwordx4 v[176:179], v147, s[28:29] offset:512
	global_load_dwordx4 v[180:183], v147, s[28:29] offset:528
	s_waitcnt vmcnt(12)
	v_pk_mul_f32 v[64:65], v[64:65], v[154:155]
	v_pk_mul_f32 v[62:63], v[62:63], v[152:153]
	v_pk_fma_f32 v[64:65], v[186:187], s[0:1], v[64:65] op_sel_hi:[1,0,1]
	v_pk_fma_f32 v[62:63], v[184:185], s[0:1], v[62:63] op_sel_hi:[1,0,1]
	v_pk_mul_f32 v[60:61], v[60:61], v[158:159]
	v_pk_mul_f32 v[58:59], v[58:59], v[156:157]
	v_pk_fma_f32 v[60:61], v[190:191], s[0:1], v[60:61] op_sel_hi:[1,0,1]
	v_pk_fma_f32 v[58:59], v[188:189], s[0:1], v[58:59] op_sel_hi:[1,0,1]
	v_pk_mul_f32 v[56:57], v[56:57], v[162:163]
	v_pk_mul_f32 v[54:55], v[54:55], v[160:161]
	v_pk_fma_f32 v[56:57], v[194:195], s[0:1], v[56:57] op_sel_hi:[1,0,1]
	v_pk_fma_f32 v[54:55], v[192:193], s[0:1], v[54:55] op_sel_hi:[1,0,1]
	v_pk_mul_f32 v[52:53], v[52:53], v[166:167]
	v_pk_mul_f32 v[50:51], v[50:51], v[164:165]
	v_pk_fma_f32 v[52:53], v[204:205], s[0:1], v[52:53] op_sel_hi:[1,0,1]
	v_pk_fma_f32 v[50:51], v[202:203], s[0:1], v[50:51] op_sel_hi:[1,0,1]
	v_add_u32_e32 v148, 0x40000, v145
	v_cvt_pk_bf16_f32 v62, v62, v63
	v_cvt_pk_bf16_f32 v63, v64, v65
	v_cvt_pk_bf16_f32 v64, v58, v59
	v_cvt_pk_bf16_f32 v65, v60, v61
	global_store_dwordx4 v148, v[62:65], s[38:39]
	v_cvt_pk_bf16_f32 v54, v54, v55
	v_cvt_pk_bf16_f32 v55, v56, v57
	v_cvt_pk_bf16_f32 v56, v50, v51
	v_cvt_pk_bf16_f32 v57, v52, v53
	global_store_dwordx4 v148, v[54:57], s[38:39] offset:256
	v_add_u32_e32 v147, 0xb0000, v144
	global_load_dwordx4 v[184:187], v147, s[28:29]
	global_load_dwordx4 v[188:191], v147, s[28:29] offset:16
	global_load_dwordx4 v[192:195], v147, s[28:29] offset:512
	global_load_dwordx4 v[202:205], v147, s[28:29] offset:528
	s_waitcnt vmcnt(12)
	v_pk_mul_f32 v[48:49], v[48:49], v[154:155]
	v_pk_mul_f32 v[46:47], v[46:47], v[152:153]
	v_pk_fma_f32 v[48:49], v[208:209], s[0:1], v[48:49] op_sel_hi:[1,0,1]
	v_pk_fma_f32 v[46:47], v[206:207], s[0:1], v[46:47] op_sel_hi:[1,0,1]
	v_pk_mul_f32 v[44:45], v[44:45], v[158:159]
	v_pk_mul_f32 v[42:43], v[42:43], v[156:157]
	v_pk_fma_f32 v[44:45], v[212:213], s[0:1], v[44:45] op_sel_hi:[1,0,1]
	v_pk_fma_f32 v[42:43], v[210:211], s[0:1], v[42:43] op_sel_hi:[1,0,1]
	v_pk_mul_f32 v[40:41], v[40:41], v[162:163]
	v_pk_mul_f32 v[38:39], v[38:39], v[160:161]
	v_pk_fma_f32 v[40:41], v[216:217], s[0:1], v[40:41] op_sel_hi:[1,0,1]
	v_pk_fma_f32 v[38:39], v[214:215], s[0:1], v[38:39] op_sel_hi:[1,0,1]
	v_pk_mul_f32 v[36:37], v[36:37], v[166:167]
	v_pk_mul_f32 v[34:35], v[34:35], v[164:165]
	v_pk_fma_f32 v[36:37], v[220:221], s[0:1], v[36:37] op_sel_hi:[1,0,1]
	v_pk_fma_f32 v[34:35], v[218:219], s[0:1], v[34:35] op_sel_hi:[1,0,1]
	v_add_u32_e32 v148, 0x48000, v145
	v_cvt_pk_bf16_f32 v46, v46, v47
	v_cvt_pk_bf16_f32 v47, v48, v49
	v_cvt_pk_bf16_f32 v48, v42, v43
	v_cvt_pk_bf16_f32 v49, v44, v45
	global_store_dwordx4 v148, v[46:49], s[38:39]
	v_cvt_pk_bf16_f32 v38, v38, v39
	v_cvt_pk_bf16_f32 v39, v40, v41
	v_cvt_pk_bf16_f32 v40, v34, v35
	v_cvt_pk_bf16_f32 v41, v36, v37
	global_store_dwordx4 v148, v[38:41], s[38:39] offset:256
	s_waitcnt vmcnt(8)
	v_pk_mul_f32 v[32:33], v[32:33], v[154:155]
	v_pk_mul_f32 v[30:31], v[30:31], v[152:153]
	v_pk_fma_f32 v[32:33], v[170:171], s[0:1], v[32:33] op_sel_hi:[1,0,1]
	v_pk_fma_f32 v[30:31], v[168:169], s[0:1], v[30:31] op_sel_hi:[1,0,1]
	v_pk_mul_f32 v[28:29], v[28:29], v[158:159]
	v_pk_mul_f32 v[26:27], v[26:27], v[156:157]
	v_pk_fma_f32 v[28:29], v[174:175], s[0:1], v[28:29] op_sel_hi:[1,0,1]
	v_pk_fma_f32 v[26:27], v[172:173], s[0:1], v[26:27] op_sel_hi:[1,0,1]
	v_pk_mul_f32 v[24:25], v[24:25], v[162:163]
	v_pk_mul_f32 v[22:23], v[22:23], v[160:161]
	v_pk_fma_f32 v[24:25], v[178:179], s[0:1], v[24:25] op_sel_hi:[1,0,1]
	v_pk_fma_f32 v[22:23], v[176:177], s[0:1], v[22:23] op_sel_hi:[1,0,1]
	v_pk_mul_f32 v[20:21], v[20:21], v[166:167]
	v_pk_mul_f32 v[18:19], v[18:19], v[164:165]
	v_pk_fma_f32 v[20:21], v[182:183], s[0:1], v[20:21] op_sel_hi:[1,0,1]
	v_pk_fma_f32 v[18:19], v[180:181], s[0:1], v[18:19] op_sel_hi:[1,0,1]
	v_add_u32_e32 v148, 0x50000, v145
	v_cvt_pk_bf16_f32 v30, v30, v31
	v_cvt_pk_bf16_f32 v31, v32, v33
	v_cvt_pk_bf16_f32 v32, v26, v27
	v_cvt_pk_bf16_f32 v33, v28, v29
	global_store_dwordx4 v148, v[30:33], s[38:39]
	v_cvt_pk_bf16_f32 v22, v22, v23
	v_cvt_pk_bf16_f32 v23, v24, v25
	v_cvt_pk_bf16_f32 v24, v18, v19
	v_cvt_pk_bf16_f32 v25, v20, v21
	global_store_dwordx4 v148, v[22:25], s[38:39] offset:256
	s_waitcnt vmcnt(4)
	v_pk_mul_f32 v[16:17], v[16:17], v[154:155]
	v_pk_mul_f32 v[14:15], v[14:15], v[152:153]
	v_pk_fma_f32 v[16:17], v[186:187], s[0:1], v[16:17] op_sel_hi:[1,0,1]
	v_pk_fma_f32 v[14:15], v[184:185], s[0:1], v[14:15] op_sel_hi:[1,0,1]
	v_pk_mul_f32 v[12:13], v[12:13], v[158:159]
	v_pk_mul_f32 v[10:11], v[10:11], v[156:157]
	v_pk_fma_f32 v[12:13], v[190:191], s[0:1], v[12:13] op_sel_hi:[1,0,1]
	v_pk_fma_f32 v[10:11], v[188:189], s[0:1], v[10:11] op_sel_hi:[1,0,1]
	v_pk_mul_f32 v[8:9], v[8:9], v[162:163]
	v_pk_mul_f32 v[6:7], v[6:7], v[160:161]
	v_pk_fma_f32 v[8:9], v[194:195], s[0:1], v[8:9] op_sel_hi:[1,0,1]
	v_pk_fma_f32 v[6:7], v[192:193], s[0:1], v[6:7] op_sel_hi:[1,0,1]
	v_pk_mul_f32 v[4:5], v[4:5], v[166:167]
	v_pk_mul_f32 v[2:3], v[2:3], v[164:165]
	v_pk_fma_f32 v[4:5], v[204:205], s[0:1], v[4:5] op_sel_hi:[1,0,1]
	v_pk_fma_f32 v[2:3], v[202:203], s[0:1], v[2:3] op_sel_hi:[1,0,1]
	v_add_u32_e32 v148, 0x58000, v145
	v_cvt_pk_bf16_f32 v14, v14, v15
	v_cvt_pk_bf16_f32 v15, v16, v17
	v_cvt_pk_bf16_f32 v16, v10, v11
	v_cvt_pk_bf16_f32 v17, v12, v13
	global_store_dwordx4 v148, v[14:17], s[38:39]
	v_cvt_pk_bf16_f32 v6, v6, v7
	v_cvt_pk_bf16_f32 v7, v8, v9
	v_cvt_pk_bf16_f32 v8, v2, v3
	v_cvt_pk_bf16_f32 v9, v4, v5
	global_store_dwordx4 v148, v[6:9], s[38:39] offset:256
	s_andn2_b64 vcc, exec, s[4:5]
	s_mov_b64 s[0:1], -1
	s_cbranch_vccnz .LBB0_809
	s_andn2_b64 vcc, exec, s[10:11]
	s_cbranch_vccnz .LBB0_808
	s_barrier
	s_branch .LBB0_808
